# DPP version with the 85 lgkmcnt waits that no longer guard an LDS operation removed from the FFN-F2 epilogue
# baseline (speedup 1.0000x reference)
.LBB0_1060:
	s_lshl_b32 s0, s3, 8
	s_add_i32 s0, s0, s60
	s_cmpk_lt_i32 s0, 0x2000
	s_movk_i32 s20, 0xfff
	v_lshl_or_b32 v192, s2, 8, v223
	s_cselect_b32 s14, s20, 0x7ff
	s_or_b32 s2, s0, 63
	s_and_b32 s1, s14, s0
	s_and_b32 s15, s14, s2
	v_or_b32_e32 v226, s0, v221
	v_mov_b64_e32 v[208:209], s[10:11]
	s_movk_i32 s26, 0x2c00
	v_ashrrev_i32_e32 v193, 31, v192
	v_mad_i64_i32 v[152:153], s[2:3], v226, s26, v[208:209]
	s_cmp_eq_u32 s1, 0
	s_mul_i32 s1, s0, 0x2c00
	v_lshlrev_b64 v[204:205], 1, v[192:193]
	s_cselect_b64 s[62:63], -1, 0
	s_mul_hi_i32 s3, s0, 0x2c00
	s_add_u32 s2, s10, s1
	v_lshl_add_u64 v[194:195], v[152:153], 0, v[204:205]
	s_mov_b32 s21, 0x2c000
	s_addc_u32 s3, s11, s3
	v_add_co_u32_e32 v198, vcc, s21, v194
	s_and_b64 s[12:13], s[62:63], exec
	s_nop 0
	v_addc_co_u32_e32 v199, vcc, 0, v195, vcc
	s_mov_b32 s22, 0x58000
	s_cselect_b32 s12, 0, 0xffffd400
	s_cselect_b32 s13, 0, -1
	s_cmp_eq_u32 s15, s14
	v_add_co_u32_e32 v200, vcc, s22, v194
	s_cselect_b64 s[50:51], -1, 0
	v_lshlrev_b64 v[88:89], 2, v[192:193]
	v_addc_co_u32_e32 v201, vcc, 0, v195, vcc
	s_mov_b32 s23, 0x84000
	v_lshl_add_u64 v[202:203], s[2:3], 0, v[204:205]
	s_and_b64 s[2:3], s[50:51], exec
	v_lshl_add_u64 v[190:191], s[18:19], 0, v[88:89]
	v_lshl_add_u64 v[90:91], s[46:47], 0, v[88:89]
	v_lshl_add_u64 v[96:97], s[48:49], 0, v[88:89]
	v_add_co_u32_e32 v206, vcc, s23, v194
	s_cselect_b32 s72, 0, 0xb0000
	v_lshl_add_u64 v[188:189], s[30:31], 0, v[88:89]
	global_load_dwordx4 v[100:103], v[190:191], off offset:16
	global_load_dwordx4 v[120:123], v[190:191], off
	global_load_dwordx4 v[92:95], v[90:91], off offset:16
	global_load_dwordx4 v[112:115], v[90:91], off
	s_nop 0
	global_load_dwordx4 v[88:91], v[96:97], off offset:16
	global_load_dwordx4 v[108:111], v[96:97], off
	s_nop 0
	global_load_dwordx4 v[96:99], v[188:189], off offset:16
	global_load_dwordx4 v[116:119], v[188:189], off
	global_load_dwordx4 v[172:175], v[194:195], off
	v_addc_co_u32_e32 v207, vcc, 0, v195, vcc
	v_lshl_add_u64 v[196:197], v[202:203], 0, s[12:13]
	v_lshl_add_u64 v[202:203], v[202:203], 0, s[72:73]
	global_load_dwordx4 v[168:171], v[198:199], off
	global_load_dwordx4 v[164:167], v[200:201], off
	global_load_dwordx4 v[152:155], v[206:207], off
	global_load_dwordx4 v[232:235], v[202:203], off
	global_load_dwordx4 v[228:231], v[196:197], off
	v_or_b32_e32 v193, v211, v219
	v_lshlrev_b32_e32 v193, 2, v193
	v_or_b32_e32 v225, v219, v212
	v_lshlrev_b32_e32 v225, 2, v225
	s_add_i32 s12, s0, 0x80
	s_cmpk_lt_i32 s12, 0x2000
	s_cselect_b32 s13, s20, 0x7ff
	s_addk_i32 s0, 0xbf
	s_and_b32 s14, s13, s12
	s_and_b32 s15, s13, s0
	s_cmp_eq_u32 s14, 0
	s_waitcnt vmcnt(0)
	v_mov_b32_dpp v239, v172 row_ror:1 row_mask:0xf bank_mask:0xf
	v_mov_b32_dpp v240, v173 row_ror:1 row_mask:0xf bank_mask:0xf
	v_mov_b32_dpp v241, v174 row_ror:1 row_mask:0xf bank_mask:0xf
	v_mov_b32_dpp v242, v175 row_ror:1 row_mask:0xf bank_mask:0xf
	v_mov_b32_dpp v243, v168 row_ror:15 row_mask:0xf bank_mask:0xf
	v_mov_b32_dpp v244, v169 row_ror:15 row_mask:0xf bank_mask:0xf
	v_mov_b32_dpp v245, v170 row_ror:15 row_mask:0xf bank_mask:0xf
	v_cndmask_b32_e64 v227, v235, 0, s[50:51]
	v_cndmask_b32_e64 v236, v230, 0, s[62:63]
	v_cndmask_b32_e64 v237, v229, 0, s[62:63]
	v_cndmask_b32_e64 v229, v233, 0, s[50:51]
	v_cndmask_b32_e64 v230, v232, 0, s[50:51]
	v_mov_b32_dpp v232, v172 row_ror:15 row_mask:0xf bank_mask:0xf
	v_mov_b32_dpp v233, v173 row_ror:15 row_mask:0xf bank_mask:0xf
	v_cndmask_b32_e64 v238, v228, 0, s[62:63]
	v_cndmask_b32_e64 v228, v234, 0, s[50:51]
	v_mov_b32_dpp v234, v174 row_ror:15 row_mask:0xf bank_mask:0xf
	v_mov_b32_dpp v235, v175 row_ror:15 row_mask:0xf bank_mask:0xf
	v_mov_b32_dpp v246, v171 row_ror:15 row_mask:0xf bank_mask:0xf
	s_waitcnt lgkmcnt(0)
	v_cndmask_b32_e64 v238, v239, v238, s[4:5]
	v_cndmask_b32_e64 v247, v232, v243, s[6:7]
	v_cndmask_b32_e64 v249, v233, v244, s[6:7]
	v_lshlrev_b32_e32 v232, 16, v238
	v_and_b32_e32 v233, 0xffff0000, v238
	v_cndmask_b32_e64 v248, v240, v237, s[4:5]
	v_cndmask_b32_e64 v250, v241, v236, s[4:5]
	v_pk_mul_f32 v[232:233], v[120:121], v[232:233]
	v_lshlrev_b32_e32 v236, 16, v172
	v_and_b32_e32 v237, 0xffff0000, v172
	v_cndmask_b32_e64 v251, v234, v245, s[6:7]
	v_cndmask_b32_e64 v252, v235, v246, s[6:7]
	v_lshlrev_b32_e32 v234, 16, v247
	v_and_b32_e32 v235, 0xffff0000, v247
	v_pk_fma_f32 v[232:233], v[112:113], v[236:237], v[232:233]
	v_cndmask_b32_e64 v231, v231, 0, s[62:63]
	v_pk_fma_f32 v[232:233], v[108:109], v[234:235], v[232:233]
	v_cndmask_b32_e64 v231, v242, v231, s[4:5]
	v_pk_add_f32 v[232:233], v[116:117], v[232:233]
	v_mov_b32_dpp v236, v166 row_ror:15 row_mask:0xf bank_mask:0xf
	v_mul_f32_e32 v172, 0xbfb8aa3b, v232
	v_exp_f32_e32 v172, v172
	v_mov_b32_dpp v237, v167 row_ror:15 row_mask:0xf bank_mask:0xf
	v_add_f32_e32 v172, 1.0, v172
	v_rcp_f32_e32 v234, v172
	v_mul_f32_e32 v172, 0xbfb8aa3b, v233
	v_exp_f32_e32 v172, v172
	s_nop 0
	v_add_f32_e32 v172, 1.0, v172
	v_rcp_f32_e32 v235, v172
	v_lshlrev_b32_e32 v172, 16, v173
	v_and_b32_e32 v173, 0xffff0000, v173
	v_pk_mul_f32 v[232:233], v[232:233], v[234:235]
	s_nop 0
	v_pk_mul_f32 v[160:161], v[160:161], v[232:233]
	v_lshlrev_b32_e32 v232, 16, v248
	v_and_b32_e32 v233, 0xffff0000, v248
	v_pk_mul_f32 v[232:233], v[122:123], v[232:233]
	v_lshlrev_b32_e32 v234, 16, v249
	v_and_b32_e32 v235, 0xffff0000, v249
	v_pk_fma_f32 v[172:173], v[114:115], v[172:173], v[232:233]
	s_nop 0
	v_pk_fma_f32 v[172:173], v[110:111], v[234:235], v[172:173]
	v_lshlrev_b32_e32 v234, 16, v174
	v_pk_add_f32 v[172:173], v[118:119], v[172:173]
	v_and_b32_e32 v235, 0xffff0000, v174
	v_mul_f32_e32 v232, 0xbfb8aa3b, v172
	v_mul_f32_e32 v233, 0xbfb8aa3b, v173
	v_exp_f32_e32 v232, v232
	v_exp_f32_e32 v233, v233
	v_add_f32_e32 v232, 1.0, v232
	v_add_f32_e32 v233, 1.0, v233
	v_rcp_f32_e32 v232, v232
	v_rcp_f32_e32 v233, v233
	s_nop 0
	v_pk_mul_f32 v[172:173], v[172:173], v[232:233]
	s_nop 0
	v_pk_mul_f32 v[162:163], v[162:163], v[172:173]
	v_lshlrev_b32_e32 v172, 16, v250
	v_and_b32_e32 v173, 0xffff0000, v250
	v_pk_mul_f32 v[172:173], v[100:101], v[172:173]
	v_lshlrev_b32_e32 v232, 16, v251
	v_and_b32_e32 v233, 0xffff0000, v251
	v_pk_fma_f32 v[172:173], v[92:93], v[234:235], v[172:173]
	v_mov_b32_dpp v234, v164 row_ror:15 row_mask:0xf bank_mask:0xf
	v_pk_fma_f32 v[172:173], v[88:89], v[232:233], v[172:173]
	v_mov_b32_dpp v235, v165 row_ror:15 row_mask:0xf bank_mask:0xf
	v_pk_add_f32 v[172:173], v[96:97], v[172:173]
	s_nop 0
	v_mul_f32_e32 v174, 0xbfb8aa3b, v172
	v_exp_f32_e32 v174, v174
	s_nop 0
	v_add_f32_e32 v174, 1.0, v174
	v_rcp_f32_e32 v232, v174
	v_mul_f32_e32 v174, 0xbfb8aa3b, v173
	v_exp_f32_e32 v174, v174
	s_nop 0
	v_add_f32_e32 v174, 1.0, v174
	v_rcp_f32_e32 v233, v174
	v_lshlrev_b32_e32 v174, 16, v175
	v_and_b32_e32 v175, 0xffff0000, v175
	v_pk_mul_f32 v[172:173], v[172:173], v[232:233]
	s_nop 0
	v_pk_mul_f32 v[156:157], v[156:157], v[172:173]
	v_lshlrev_b32_e32 v172, 16, v231
	v_and_b32_e32 v173, 0xffff0000, v231
	v_pk_mul_f32 v[172:173], v[102:103], v[172:173]
	v_lshlrev_b32_e32 v232, 16, v252
	v_and_b32_e32 v233, 0xffff0000, v252
	v_pk_fma_f32 v[172:173], v[94:95], v[174:175], v[172:173]
	v_mov_b32_dpp v231, v170 row_ror:1 row_mask:0xf bank_mask:0xf
	v_pk_fma_f32 v[172:173], v[90:91], v[232:233], v[172:173]
	v_mov_b32_dpp v232, v171 row_ror:1 row_mask:0xf bank_mask:0xf
	v_pk_add_f32 v[172:173], v[98:99], v[172:173]
	v_or_b32_e32 v233, 16, v226
	v_mul_f32_e32 v174, 0xbfb8aa3b, v172
	v_mul_f32_e32 v175, 0xbfb8aa3b, v173
	v_exp_f32_e32 v174, v174
	v_exp_f32_e32 v175, v175
	v_cndmask_b32_e64 v242, v232, v242, s[4:5]
	v_add_f32_e32 v174, 1.0, v174
	v_add_f32_e32 v175, 1.0, v175
	v_rcp_f32_e32 v174, v174
	v_rcp_f32_e32 v175, v175
	s_nop 0
	v_pk_mul_f32 v[172:173], v[172:173], v[174:175]
	v_mov_b32_dpp v174, v168 row_ror:1 row_mask:0xf bank_mask:0xf
	v_pk_mul_f32 v[172:173], v[158:159], v[172:173]
	v_cvt_pk_bf16_f32 v158, v160, v161
	v_cvt_pk_bf16_f32 v161, v172, v173
	v_mov_b64_e32 v[172:173], s[16:17]
	v_cvt_pk_bf16_f32 v160, v156, v157
	v_mad_i64_i32 v[156:157], s[2:3], v226, s26, v[172:173]
	v_cvt_pk_bf16_f32 v159, v162, v163
	v_lshl_add_u64 v[156:157], v[156:157], 0, v[204:205]
	global_store_dwordx4 v[156:157], v[158:161], off
	v_lshlrev_b32_e32 v162, 16, v168
	v_and_b32_e32 v163, 0xffff0000, v168
	v_cndmask_b32_e64 v159, v174, v239, s[4:5]
	v_lshlrev_b32_e32 v158, 16, v159
	v_and_b32_e32 v159, 0xffff0000, v159
	v_cndmask_b32_e64 v161, v243, v234, s[6:7]
	v_pk_mul_f32 v[158:159], v[120:121], v[158:159]
	v_lshlrev_b32_e32 v160, 16, v161
	v_and_b32_e32 v161, 0xffff0000, v161
	v_pk_fma_f32 v[158:159], v[112:113], v[162:163], v[158:159]
	v_mov_b32_dpp v175, v169 row_ror:1 row_mask:0xf bank_mask:0xf
	v_pk_fma_f32 v[158:159], v[108:109], v[160:161], v[158:159]
	v_cndmask_b32_e64 v239, v244, v235, s[6:7]
	v_pk_add_f32 v[158:159], v[116:117], v[158:159]
	v_lshlrev_b32_e32 v162, 16, v169
	v_mul_f32_e32 v160, 0xbfb8aa3b, v158
	v_mul_f32_e32 v161, 0xbfb8aa3b, v159
	v_exp_f32_e32 v160, v160
	v_exp_f32_e32 v161, v161
	v_cndmask_b32_e64 v238, v175, v240, s[4:5]
	v_and_b32_e32 v163, 0xffff0000, v169
	v_add_f32_e32 v160, 1.0, v160
	v_add_f32_e32 v161, 1.0, v161
	v_rcp_f32_e32 v160, v160
	v_rcp_f32_e32 v161, v161
	v_cndmask_b32_e64 v240, v231, v241, s[4:5]
	v_cndmask_b32_e64 v241, v245, v236, s[6:7]
	v_cndmask_b32_e64 v243, v246, v237, s[6:7]
	v_pk_mul_f32 v[158:159], v[158:159], v[160:161]
	v_lshlrev_b32_e32 v160, 16, v239
	v_pk_mul_f32 v[148:149], v[148:149], v[158:159]
	v_lshlrev_b32_e32 v158, 16, v238
	v_and_b32_e32 v159, 0xffff0000, v238
	v_pk_mul_f32 v[158:159], v[122:123], v[158:159]
	v_and_b32_e32 v161, 0xffff0000, v239
	v_pk_fma_f32 v[158:159], v[114:115], v[162:163], v[158:159]
	v_lshlrev_b32_e32 v162, 16, v170
	v_pk_fma_f32 v[158:159], v[110:111], v[160:161], v[158:159]
	v_and_b32_e32 v163, 0xffff0000, v170
	v_pk_add_f32 v[158:159], v[118:119], v[158:159]
	v_cvt_pk_bf16_f32 v148, v148, v149
	v_mul_f32_e32 v160, 0xbfb8aa3b, v158
	v_mul_f32_e32 v161, 0xbfb8aa3b, v159
	v_exp_f32_e32 v160, v160
	v_exp_f32_e32 v161, v161
	v_mov_b32_dpp v168, v153 row_ror:15 row_mask:0xf bank_mask:0xf
	v_mov_b32_dpp v169, v154 row_ror:15 row_mask:0xf bank_mask:0xf
	v_add_f32_e32 v160, 1.0, v160
	v_add_f32_e32 v161, 1.0, v161
	v_rcp_f32_e32 v160, v160
	v_rcp_f32_e32 v161, v161
	v_mov_b32_dpp v170, v155 row_ror:15 row_mask:0xf bank_mask:0xf
	v_pk_mul_f32 v[158:159], v[158:159], v[160:161]
	s_nop 0
	v_pk_mul_f32 v[150:151], v[150:151], v[158:159]
	v_lshlrev_b32_e32 v158, 16, v240
	v_and_b32_e32 v159, 0xffff0000, v240
	v_pk_mul_f32 v[158:159], v[100:101], v[158:159]
	v_lshlrev_b32_e32 v160, 16, v241
	v_and_b32_e32 v161, 0xffff0000, v241
	v_pk_fma_f32 v[158:159], v[92:93], v[162:163], v[158:159]
	v_lshlrev_b32_e32 v162, 16, v171
	v_pk_fma_f32 v[158:159], v[88:89], v[160:161], v[158:159]
	v_and_b32_e32 v163, 0xffff0000, v171
	v_pk_add_f32 v[158:159], v[96:97], v[158:159]
	v_cvt_pk_bf16_f32 v149, v150, v151
	v_mul_f32_e32 v160, 0xbfb8aa3b, v158
	v_mul_f32_e32 v161, 0xbfb8aa3b, v159
	v_exp_f32_e32 v160, v160
	v_exp_f32_e32 v161, v161
	v_add_f32_e32 v160, 1.0, v160
	v_add_f32_e32 v161, 1.0, v161
	v_rcp_f32_e32 v160, v160
	v_rcp_f32_e32 v161, v161
	s_nop 0
	v_pk_mul_f32 v[158:159], v[158:159], v[160:161]
	s_nop 0
	v_pk_mul_f32 v[144:145], v[144:145], v[158:159]
	v_lshlrev_b32_e32 v158, 16, v242
	v_and_b32_e32 v159, 0xffff0000, v242
	v_pk_mul_f32 v[158:159], v[102:103], v[158:159]
	v_lshlrev_b32_e32 v160, 16, v243
	v_and_b32_e32 v161, 0xffff0000, v243
	v_pk_fma_f32 v[158:159], v[94:95], v[162:163], v[158:159]
	v_mov_b32_dpp v163, v152 row_ror:15 row_mask:0xf bank_mask:0xf
	v_pk_fma_f32 v[158:159], v[90:91], v[160:161], v[158:159]
	v_cvt_pk_bf16_f32 v150, v144, v145
	v_pk_add_f32 v[158:159], v[98:99], v[158:159]
	v_mad_i64_i32 v[144:145], s[2:3], v233, s26, v[172:173]
	v_mul_f32_e32 v160, 0xbfb8aa3b, v158
	v_mul_f32_e32 v161, 0xbfb8aa3b, v159
	v_exp_f32_e32 v160, v160
	v_exp_f32_e32 v161, v161
	v_cndmask_b32_e64 v233, v237, v170, s[6:7]
	v_or_b32_e32 v162, 32, v226
	v_add_f32_e32 v160, 1.0, v160
	v_add_f32_e32 v161, 1.0, v161
	v_rcp_f32_e32 v160, v160
	v_rcp_f32_e32 v161, v161
	s_nop 0
	v_pk_mul_f32 v[158:159], v[158:159], v[160:161]
	s_nop 0
	v_pk_mul_f32 v[146:147], v[146:147], v[158:159]
	v_mov_b32_dpp v158, v164 row_ror:1 row_mask:0xf bank_mask:0xf
	v_cvt_pk_bf16_f32 v151, v146, v147
	v_lshl_add_u64 v[146:147], v[144:145], 0, v[204:205]
	global_store_dwordx4 v[146:147], v[148:151], off
	v_mov_b32_dpp v159, v165 row_ror:1 row_mask:0xf bank_mask:0xf
	v_cndmask_b32_e64 v145, v158, v174, s[4:5]
	v_lshlrev_b32_e32 v144, 16, v145
	v_and_b32_e32 v145, 0xffff0000, v145
	v_cndmask_b32_e64 v149, v234, v163, s[6:7]
	v_pk_mul_f32 v[144:145], v[120:121], v[144:145]
	v_lshlrev_b32_e32 v150, 16, v164
	v_and_b32_e32 v151, 0xffff0000, v164
	v_lshlrev_b32_e32 v148, 16, v149
	v_and_b32_e32 v149, 0xffff0000, v149
	v_pk_fma_f32 v[144:145], v[112:113], v[150:151], v[144:145]
	v_cndmask_b32_e64 v171, v159, v175, s[4:5]
	v_pk_fma_f32 v[144:145], v[108:109], v[148:149], v[144:145]
	v_cndmask_b32_e64 v174, v235, v168, s[6:7]
	v_pk_add_f32 v[144:145], v[116:117], v[144:145]
	v_lshlrev_b32_e32 v150, 16, v165
	v_mul_f32_e32 v148, 0xbfb8aa3b, v144
	v_mul_f32_e32 v149, 0xbfb8aa3b, v145
	v_exp_f32_e32 v148, v148
	v_exp_f32_e32 v149, v149
	v_and_b32_e32 v151, 0xffff0000, v165
	v_mov_b32_dpp v160, v166 row_ror:1 row_mask:0xf bank_mask:0xf
	v_add_f32_e32 v148, 1.0, v148
	v_add_f32_e32 v149, 1.0, v149
	v_rcp_f32_e32 v148, v148
	v_rcp_f32_e32 v149, v149
	v_cndmask_b32_e64 v175, v160, v231, s[4:5]
	v_cndmask_b32_e64 v231, v236, v169, s[6:7]
	v_mov_b32_dpp v161, v167 row_ror:1 row_mask:0xf bank_mask:0xf
	v_pk_mul_f32 v[144:145], v[144:145], v[148:149]
	v_lshlrev_b32_e32 v148, 16, v174
	v_pk_mul_f32 v[140:141], v[140:141], v[144:145]
	v_lshlrev_b32_e32 v144, 16, v171
	v_and_b32_e32 v145, 0xffff0000, v171
	v_pk_mul_f32 v[144:145], v[122:123], v[144:145]
	v_and_b32_e32 v149, 0xffff0000, v174
	v_pk_fma_f32 v[144:145], v[114:115], v[150:151], v[144:145]
	v_lshlrev_b32_e32 v150, 16, v166
	v_pk_fma_f32 v[144:145], v[110:111], v[148:149], v[144:145]
	v_and_b32_e32 v151, 0xffff0000, v166
	v_pk_add_f32 v[144:145], v[118:119], v[144:145]
	v_cndmask_b32_e64 v232, v161, v232, s[4:5]
	v_mul_f32_e32 v148, 0xbfb8aa3b, v144
	v_mul_f32_e32 v149, 0xbfb8aa3b, v145
	v_exp_f32_e32 v148, v148
	v_exp_f32_e32 v149, v149
	v_or_b32_e32 v164, s12, v221
	v_add_f32_e32 v148, 1.0, v148
	v_add_f32_e32 v149, 1.0, v149
	v_rcp_f32_e32 v148, v148
	v_rcp_f32_e32 v149, v149
	s_nop 0
	v_pk_mul_f32 v[144:145], v[144:145], v[148:149]
	s_nop 0
	v_pk_mul_f32 v[142:143], v[142:143], v[144:145]
	v_lshlrev_b32_e32 v144, 16, v175
	v_and_b32_e32 v145, 0xffff0000, v175
	v_pk_mul_f32 v[144:145], v[100:101], v[144:145]
	v_lshlrev_b32_e32 v148, 16, v231
	v_and_b32_e32 v149, 0xffff0000, v231
	v_pk_fma_f32 v[144:145], v[92:93], v[150:151], v[144:145]
	v_lshlrev_b32_e32 v150, 16, v167
	v_pk_fma_f32 v[144:145], v[88:89], v[148:149], v[144:145]
	v_and_b32_e32 v151, 0xffff0000, v167
	v_pk_add_f32 v[144:145], v[96:97], v[144:145]
	s_nop 0
	v_mul_f32_e32 v148, 0xbfb8aa3b, v144
	v_mul_f32_e32 v149, 0xbfb8aa3b, v145
	v_exp_f32_e32 v148, v148
	v_exp_f32_e32 v149, v149
	v_add_f32_e32 v148, 1.0, v148
	v_add_f32_e32 v149, 1.0, v149
	v_rcp_f32_e32 v148, v148
	v_rcp_f32_e32 v149, v149
	s_nop 0
	v_pk_mul_f32 v[144:145], v[144:145], v[148:149]
	s_nop 0
	v_pk_mul_f32 v[144:145], v[136:137], v[144:145]
	v_lshlrev_b32_e32 v136, 16, v232
	v_and_b32_e32 v137, 0xffff0000, v232
	v_pk_mul_f32 v[136:137], v[102:103], v[136:137]
	v_lshlrev_b32_e32 v148, 16, v233
	v_and_b32_e32 v149, 0xffff0000, v233
	v_pk_fma_f32 v[136:137], v[94:95], v[150:151], v[136:137]
	v_cndmask_b32_e64 v150, v169, v228, s[6:7]
	v_pk_fma_f32 v[136:137], v[90:91], v[148:149], v[136:137]
	s_nop 0
	v_pk_add_f32 v[136:137], v[98:99], v[136:137]
	s_nop 0
	v_mul_f32_e32 v148, 0xbfb8aa3b, v136
	v_mul_f32_e32 v149, 0xbfb8aa3b, v137
	v_exp_f32_e32 v148, v148
	v_exp_f32_e32 v149, v149
	v_add_f32_e32 v148, 1.0, v148
	v_add_f32_e32 v149, 1.0, v149
	v_rcp_f32_e32 v148, v148
	v_rcp_f32_e32 v149, v149
	s_nop 0
	v_pk_mul_f32 v[136:137], v[136:137], v[148:149]
	s_nop 0
	v_pk_mul_f32 v[148:149], v[138:139], v[136:137]
	v_cvt_pk_bf16_f32 v136, v140, v141
	v_mad_i64_i32 v[140:141], s[2:3], v162, s26, v[172:173]
	v_cvt_pk_bf16_f32 v137, v142, v143
	v_cvt_pk_bf16_f32 v138, v144, v145
	v_cvt_pk_bf16_f32 v139, v148, v149
	v_lshl_add_u64 v[148:149], v[140:141], 0, v[204:205]
	global_store_dwordx4 v[148:149], v[136:139], off
	ds_bpermute_b32 v136, v193, v152
	ds_bpermute_b32 v137, v193, v153
	v_mov_b32_dpp v138, v154 row_ror:1 row_mask:0xf bank_mask:0xf
	v_mov_b32_dpp v139, v155 row_ror:1 row_mask:0xf bank_mask:0xf
	v_cndmask_b32_e64 v141, v163, v230, s[6:7]
	s_waitcnt lgkmcnt(0)
	v_cndmask_b32_e64 v140, v136, v158, s[4:5]
	v_cndmask_b32_e64 v143, v137, v159, s[4:5]
	v_lshlrev_b32_e32 v136, 16, v140
	v_and_b32_e32 v137, 0xffff0000, v140
	v_cndmask_b32_e64 v145, v138, v160, s[4:5]
	v_cndmask_b32_e64 v151, v139, v161, s[4:5]
	v_lshlrev_b32_e32 v138, 16, v141
	v_and_b32_e32 v139, 0xffff0000, v141
	v_pk_mul_f32 v[136:137], v[120:121], v[136:137]
	v_lshlrev_b32_e32 v140, 16, v152
	v_and_b32_e32 v141, 0xffff0000, v152
	v_pk_fma_f32 v[136:137], v[112:113], v[140:141], v[136:137]
	v_cndmask_b32_e64 v144, v168, v229, s[6:7]
	v_pk_fma_f32 v[136:137], v[108:109], v[138:139], v[136:137]
	v_lshlrev_b32_e32 v140, 16, v153
	v_pk_add_f32 v[136:137], v[116:117], v[136:137]
	v_and_b32_e32 v141, 0xffff0000, v153
	v_mul_f32_e32 v138, 0xbfb8aa3b, v136
	v_mul_f32_e32 v139, 0xbfb8aa3b, v137
	v_exp_f32_e32 v138, v138
	v_exp_f32_e32 v139, v139
	v_cndmask_b32_e64 v158, v170, v227, s[6:7]
	v_or_b32_e32 v142, 48, v226
	v_add_f32_e32 v138, 1.0, v138
	v_add_f32_e32 v139, 1.0, v139
	v_rcp_f32_e32 v138, v138
	v_rcp_f32_e32 v139, v139
	s_nop 0
	v_pk_mul_f32 v[136:137], v[136:137], v[138:139]
	s_nop 0
	v_pk_mul_f32 v[132:133], v[132:133], v[136:137]
	v_lshlrev_b32_e32 v136, 16, v143
	v_and_b32_e32 v137, 0xffff0000, v143
	v_pk_mul_f32 v[136:137], v[122:123], v[136:137]
	v_lshlrev_b32_e32 v138, 16, v144
	v_and_b32_e32 v139, 0xffff0000, v144
	v_pk_fma_f32 v[136:137], v[114:115], v[140:141], v[136:137]
	v_lshlrev_b32_e32 v140, 16, v154
	v_pk_fma_f32 v[136:137], v[110:111], v[138:139], v[136:137]
	v_and_b32_e32 v141, 0xffff0000, v154
	v_pk_add_f32 v[136:137], v[118:119], v[136:137]
	s_nop 0
	v_mul_f32_e32 v138, 0xbfb8aa3b, v136
	v_mul_f32_e32 v139, 0xbfb8aa3b, v137
	v_exp_f32_e32 v138, v138
	v_exp_f32_e32 v139, v139
	v_add_f32_e32 v138, 1.0, v138
	v_add_f32_e32 v139, 1.0, v139
	v_rcp_f32_e32 v138, v138
	v_rcp_f32_e32 v139, v139
	s_nop 0
	v_pk_mul_f32 v[136:137], v[136:137], v[138:139]
	s_nop 0
	v_pk_mul_f32 v[134:135], v[134:135], v[136:137]
	v_lshlrev_b32_e32 v136, 16, v145
	v_and_b32_e32 v137, 0xffff0000, v145
	v_pk_mul_f32 v[136:137], v[100:101], v[136:137]
	v_lshlrev_b32_e32 v138, 16, v150
	v_and_b32_e32 v139, 0xffff0000, v150
	v_pk_fma_f32 v[136:137], v[92:93], v[140:141], v[136:137]
	v_lshlrev_b32_e32 v140, 16, v155
	v_pk_fma_f32 v[136:137], v[88:89], v[138:139], v[136:137]
	v_and_b32_e32 v141, 0xffff0000, v155
	v_pk_add_f32 v[136:137], v[96:97], v[136:137]
	s_nop 0
	v_mul_f32_e32 v138, 0xbfb8aa3b, v136
	v_mul_f32_e32 v139, 0xbfb8aa3b, v137
	v_exp_f32_e32 v138, v138
	v_exp_f32_e32 v139, v139
	v_add_f32_e32 v138, 1.0, v138
	v_add_f32_e32 v139, 1.0, v139
	v_rcp_f32_e32 v138, v138
	v_rcp_f32_e32 v139, v139
	s_nop 0
	v_pk_mul_f32 v[136:137], v[136:137], v[138:139]
	s_nop 0
	v_pk_mul_f32 v[136:137], v[128:129], v[136:137]
	v_lshlrev_b32_e32 v128, 16, v151
	v_and_b32_e32 v129, 0xffff0000, v151
	v_pk_mul_f32 v[128:129], v[102:103], v[128:129]
	v_lshlrev_b32_e32 v138, 16, v158
	v_and_b32_e32 v139, 0xffff0000, v158
	v_pk_fma_f32 v[128:129], v[94:95], v[140:141], v[128:129]
	s_nop 0
	v_pk_fma_f32 v[128:129], v[90:91], v[138:139], v[128:129]
	s_nop 0
	v_pk_add_f32 v[128:129], v[98:99], v[128:129]
	s_nop 0
	v_mul_f32_e32 v138, 0xbfb8aa3b, v128
	v_mul_f32_e32 v139, 0xbfb8aa3b, v129
	v_exp_f32_e32 v138, v138
	v_exp_f32_e32 v139, v139
	v_add_f32_e32 v138, 1.0, v138
	v_add_f32_e32 v139, 1.0, v139
	v_rcp_f32_e32 v138, v138
	v_rcp_f32_e32 v139, v139
	s_nop 0
	v_pk_mul_f32 v[128:129], v[128:129], v[138:139]
	s_nop 0
	v_pk_mul_f32 v[138:139], v[130:131], v[128:129]
	v_cvt_pk_bf16_f32 v128, v132, v133
	v_mad_i64_i32 v[132:133], s[2:3], v142, s26, v[172:173]
	v_cvt_pk_bf16_f32 v129, v134, v135
	v_cvt_pk_bf16_f32 v130, v136, v137
	v_cvt_pk_bf16_f32 v131, v138, v139
	v_lshl_add_u64 v[144:145], v[132:133], 0, v[204:205]
	global_store_dwordx4 v[144:145], v[128:131], off
	s_nop 1
	v_mad_i64_i32 v[128:129], s[2:3], v164, s26, v[208:209]
	v_lshl_add_u64 v[150:151], v[128:129], 0, v[204:205]
	v_add_co_u32_e32 v152, vcc, s21, v150
	s_mul_hi_i32 s2, s12, 0x2c00
	s_nop 0
	v_addc_co_u32_e32 v153, vcc, 0, v151, vcc
	v_add_co_u32_e32 v154, vcc, s22, v150
	global_load_dwordx4 v[140:143], v[150:151], off
	global_load_dwordx4 v[136:139], v[152:153], off
	v_addc_co_u32_e32 v155, vcc, 0, v151, vcc
	v_add_co_u32_e32 v158, vcc, s23, v150
	s_cselect_b64 s[22:23], -1, 0
	s_add_i32 s1, s1, 0x160000
	s_add_u32 s0, s10, s1
	s_addc_u32 s1, s11, s2
	s_and_b64 s[2:3], s[22:23], exec
	v_addc_co_u32_e32 v159, vcc, 0, v151, vcc
	s_cselect_b32 s2, 0, 0xffffd400
	s_cselect_b32 s3, 0, -1
	s_cmp_eq_u32 s15, s13
	s_cselect_b64 vcc, -1, 0
	v_lshl_add_u64 v[160:161], s[0:1], 0, v[204:205]
	s_and_b64 s[0:1], vcc, exec
	s_cselect_b32 s72, 0, 0xb0000
	v_lshl_add_u64 v[162:163], v[160:161], 0, s[2:3]
	v_lshl_add_u64 v[160:161], v[160:161], 0, s[72:73]
	global_load_dwordx4 v[166:169], v[162:163], off
	global_load_dwordx4 v[226:229], v[160:161], off
	global_load_dwordx4 v[132:135], v[154:155], off
	global_load_dwordx4 v[128:131], v[158:159], off
	s_waitcnt vmcnt(5)
	v_mov_b32_dpp v175, v140 row_ror:15 row_mask:0xf bank_mask:0xf
	v_mov_b32_dpp v208, v141 row_ror:15 row_mask:0xf bank_mask:0xf
	v_mov_b32_dpp v209, v142 row_ror:15 row_mask:0xf bank_mask:0xf
	s_waitcnt vmcnt(4)
	v_mov_b32_dpp v231, v136 row_ror:15 row_mask:0xf bank_mask:0xf
	v_mov_b32_dpp v232, v137 row_ror:15 row_mask:0xf bank_mask:0xf
	v_mov_b32_dpp v233, v138 row_ror:15 row_mask:0xf bank_mask:0xf
	v_mov_b32_dpp v230, v143 row_ror:15 row_mask:0xf bank_mask:0xf
	v_mov_b32_dpp v234, v139 row_ror:15 row_mask:0xf bank_mask:0xf
	v_cndmask_b32_e64 v175, v175, v231, s[6:7]
	v_cndmask_b32_e64 v237, v208, v232, s[6:7]
	v_cndmask_b32_e64 v239, v209, v233, s[6:7]
	v_lshlrev_b32_e32 v208, 16, v140
	v_and_b32_e32 v209, 0xffff0000, v140
	v_cndmask_b32_e64 v230, v230, v234, s[6:7]
	s_waitcnt vmcnt(3)
	v_cndmask_b32_e64 v170, v168, 0, s[22:23]
	s_waitcnt vmcnt(2)
	v_cndmask_b32_e64 v168, v226, 0, vcc
	v_mov_b32_dpp v226, v140 row_ror:1 row_mask:0xf bank_mask:0xf
	v_cndmask_b32_e64 v171, v167, 0, s[22:23]
	v_cndmask_b32_e64 v174, v166, 0, s[22:23]
	v_cndmask_b32_e64 v166, v228, 0, vcc
	v_cndmask_b32_e64 v167, v227, 0, vcc
	v_mov_b32_dpp v227, v141 row_ror:1 row_mask:0xf bank_mask:0xf
	v_mov_b32_dpp v228, v142 row_ror:1 row_mask:0xf bank_mask:0xf
	v_cndmask_b32_e64 v235, v226, v174, s[4:5]
	v_lshlrev_b32_e32 v174, 16, v175
	v_and_b32_e32 v175, 0xffff0000, v175
	v_cndmask_b32_e64 v236, v227, v171, s[4:5]
	v_cndmask_b32_e64 v238, v228, v170, s[4:5]
	v_lshlrev_b32_e32 v170, 16, v235
	v_and_b32_e32 v171, 0xffff0000, v235
	v_pk_mul_f32 v[170:171], v[120:121], v[170:171]
	v_cndmask_b32_e64 v165, v229, 0, vcc
	v_pk_fma_f32 v[170:171], v[112:113], v[208:209], v[170:171]
	v_mov_b32_dpp v229, v143 row_ror:1 row_mask:0xf bank_mask:0xf
	v_pk_fma_f32 v[170:171], v[108:109], v[174:175], v[170:171]
	v_cndmask_b32_e64 v169, v169, 0, s[22:23]
	v_pk_add_f32 v[170:171], v[116:117], v[170:171]
	v_cndmask_b32_e64 v169, v229, v169, s[4:5]
	v_mul_f32_e32 v140, 0xbfb8aa3b, v170
	v_exp_f32_e32 v140, v140
	s_nop 0
	v_add_f32_e32 v140, 1.0, v140
	v_rcp_f32_e32 v174, v140
	v_mul_f32_e32 v140, 0xbfb8aa3b, v171
	v_exp_f32_e32 v140, v140
	s_nop 0
	v_add_f32_e32 v140, 1.0, v140
	v_rcp_f32_e32 v175, v140
	v_lshlrev_b32_e32 v140, 16, v141
	v_and_b32_e32 v141, 0xffff0000, v141
	v_pk_mul_f32 v[170:171], v[170:171], v[174:175]
	s_nop 0
	v_pk_mul_f32 v[124:125], v[124:125], v[170:171]
	v_lshlrev_b32_e32 v170, 16, v236
	v_and_b32_e32 v171, 0xffff0000, v236
	v_pk_mul_f32 v[170:171], v[122:123], v[170:171]
	v_lshlrev_b32_e32 v174, 16, v237
	v_and_b32_e32 v175, 0xffff0000, v237
	v_pk_fma_f32 v[140:141], v[114:115], v[140:141], v[170:171]
	s_nop 0
	v_pk_fma_f32 v[140:141], v[110:111], v[174:175], v[140:141]
	v_lshlrev_b32_e32 v174, 16, v142
	v_pk_add_f32 v[140:141], v[118:119], v[140:141]
	v_and_b32_e32 v175, 0xffff0000, v142
	v_mul_f32_e32 v170, 0xbfb8aa3b, v140
	v_mul_f32_e32 v171, 0xbfb8aa3b, v141
	v_exp_f32_e32 v170, v170
	v_exp_f32_e32 v171, v171
	v_add_f32_e32 v170, 1.0, v170
	v_add_f32_e32 v171, 1.0, v171
	v_rcp_f32_e32 v170, v170
	v_rcp_f32_e32 v171, v171
	s_nop 0
	v_pk_mul_f32 v[140:141], v[140:141], v[170:171]
	s_nop 0
	v_pk_mul_f32 v[126:127], v[126:127], v[140:141]
	v_lshlrev_b32_e32 v140, 16, v238
	v_and_b32_e32 v141, 0xffff0000, v238
	v_pk_mul_f32 v[140:141], v[100:101], v[140:141]
	v_lshlrev_b32_e32 v170, 16, v239
	v_and_b32_e32 v171, 0xffff0000, v239
	v_pk_fma_f32 v[140:141], v[92:93], v[174:175], v[140:141]
	s_waitcnt vmcnt(1)
	v_mov_b32_dpp v174, v134 row_ror:15 row_mask:0xf bank_mask:0xf
	v_pk_fma_f32 v[140:141], v[88:89], v[170:171], v[140:141]
	v_mov_b32_dpp v175, v135 row_ror:15 row_mask:0xf bank_mask:0xf
	v_pk_add_f32 v[140:141], v[96:97], v[140:141]
	s_nop 0
	v_mul_f32_e32 v142, 0xbfb8aa3b, v140
	v_exp_f32_e32 v142, v142
	s_nop 0
	v_add_f32_e32 v142, 1.0, v142
	v_rcp_f32_e32 v170, v142
	v_mul_f32_e32 v142, 0xbfb8aa3b, v141
	v_exp_f32_e32 v142, v142
	s_nop 0
	v_add_f32_e32 v142, 1.0, v142
	v_rcp_f32_e32 v171, v142
	v_lshlrev_b32_e32 v142, 16, v143
	v_and_b32_e32 v143, 0xffff0000, v143
	v_pk_mul_f32 v[140:141], v[140:141], v[170:171]
	s_nop 0
	v_pk_mul_f32 v[140:141], v[104:105], v[140:141]
	v_lshlrev_b32_e32 v104, 16, v169
	v_and_b32_e32 v105, 0xffff0000, v169
	v_pk_mul_f32 v[104:105], v[102:103], v[104:105]
	v_lshlrev_b32_e32 v170, 16, v230
	v_and_b32_e32 v171, 0xffff0000, v230
	v_pk_fma_f32 v[104:105], v[94:95], v[142:143], v[104:105]
	v_or_b32_e32 v169, 16, v164
	v_pk_fma_f32 v[104:105], v[90:91], v[170:171], v[104:105]
	v_mov_b32_dpp v170, v132 row_ror:15 row_mask:0xf bank_mask:0xf
	v_pk_add_f32 v[104:105], v[98:99], v[104:105]
	v_mov_b32_dpp v171, v133 row_ror:15 row_mask:0xf bank_mask:0xf
	v_mul_f32_e32 v142, 0xbfb8aa3b, v104
	v_mul_f32_e32 v143, 0xbfb8aa3b, v105
	v_exp_f32_e32 v142, v142
	v_exp_f32_e32 v143, v143
	v_cndmask_b32_e64 v209, v232, v171, s[6:7]
	v_add_f32_e32 v142, 1.0, v142
	v_add_f32_e32 v143, 1.0, v143
	v_rcp_f32_e32 v142, v142
	v_rcp_f32_e32 v143, v143
	s_nop 0
	v_pk_mul_f32 v[104:105], v[104:105], v[142:143]
	s_nop 0
	v_pk_mul_f32 v[142:143], v[106:107], v[104:105]
	v_cvt_pk_bf16_f32 v106, v140, v141
	v_mov_b32_dpp v140, v136 row_ror:1 row_mask:0xf bank_mask:0xf
	v_cvt_pk_bf16_f32 v104, v124, v125
	v_mad_i64_i32 v[124:125], s[0:1], v164, s26, v[172:173]
	v_cvt_pk_bf16_f32 v105, v126, v127
	v_cvt_pk_bf16_f32 v107, v142, v143
	v_lshl_add_u64 v[124:125], v[124:125], 0, v[204:205]
	global_store_dwordx4 v[124:125], v[104:107], off
	v_lshlrev_b32_e32 v126, 16, v136
	v_and_b32_e32 v127, 0xffff0000, v136
	v_cndmask_b32_e64 v105, v140, v226, s[4:5]
	v_lshlrev_b32_e32 v104, 16, v105
	v_and_b32_e32 v105, 0xffff0000, v105
	v_cndmask_b32_e64 v107, v231, v170, s[6:7]
	v_pk_mul_f32 v[104:105], v[120:121], v[104:105]
	v_lshlrev_b32_e32 v106, 16, v107
	v_and_b32_e32 v107, 0xffff0000, v107
	v_pk_fma_f32 v[104:105], v[112:113], v[126:127], v[104:105]
	v_mov_b32_dpp v141, v137 row_ror:1 row_mask:0xf bank_mask:0xf
	v_pk_fma_f32 v[104:105], v[108:109], v[106:107], v[104:105]
	v_lshlrev_b32_e32 v126, 16, v137
	v_pk_add_f32 v[104:105], v[116:117], v[104:105]
	v_and_b32_e32 v127, 0xffff0000, v137
	v_mul_f32_e32 v106, 0xbfb8aa3b, v104
	v_mul_f32_e32 v107, 0xbfb8aa3b, v105
	v_exp_f32_e32 v106, v106
	v_exp_f32_e32 v107, v107
	v_cndmask_b32_e64 v208, v141, v227, s[4:5]
	v_mov_b32_dpp v142, v138 row_ror:1 row_mask:0xf bank_mask:0xf
	v_add_f32_e32 v106, 1.0, v106
	v_add_f32_e32 v107, 1.0, v107
	v_rcp_f32_e32 v106, v106
	v_rcp_f32_e32 v107, v107
	v_cndmask_b32_e64 v226, v142, v228, s[4:5]
	v_cndmask_b32_e64 v227, v233, v174, s[6:7]
	v_mov_b32_dpp v143, v139 row_ror:1 row_mask:0xf bank_mask:0xf
	v_pk_mul_f32 v[104:105], v[104:105], v[106:107]
	v_lshlrev_b32_e32 v106, 16, v209
	v_pk_mul_f32 v[84:85], v[84:85], v[104:105]
	v_lshlrev_b32_e32 v104, 16, v208
	v_and_b32_e32 v105, 0xffff0000, v208
	v_pk_mul_f32 v[104:105], v[122:123], v[104:105]
	v_and_b32_e32 v107, 0xffff0000, v209
	v_pk_fma_f32 v[104:105], v[114:115], v[126:127], v[104:105]
	v_lshlrev_b32_e32 v126, 16, v138
	v_pk_fma_f32 v[104:105], v[110:111], v[106:107], v[104:105]
	v_and_b32_e32 v127, 0xffff0000, v138
	v_pk_add_f32 v[104:105], v[118:119], v[104:105]
	v_cndmask_b32_e64 v228, v143, v229, s[4:5]
	v_mul_f32_e32 v106, 0xbfb8aa3b, v104
	v_mul_f32_e32 v107, 0xbfb8aa3b, v105
	v_exp_f32_e32 v106, v106
	v_exp_f32_e32 v107, v107
	v_cndmask_b32_e64 v229, v234, v175, s[6:7]
	s_waitcnt vmcnt(1)
	v_mov_b32_dpp v136, v129 row_ror:15 row_mask:0xf bank_mask:0xf
	v_add_f32_e32 v106, 1.0, v106
	v_add_f32_e32 v107, 1.0, v107
	v_rcp_f32_e32 v106, v106
	v_rcp_f32_e32 v107, v107
	v_mov_b32_dpp v137, v130 row_ror:15 row_mask:0xf bank_mask:0xf
	v_mov_b32_dpp v138, v131 row_ror:15 row_mask:0xf bank_mask:0xf
	v_pk_mul_f32 v[104:105], v[104:105], v[106:107]
	s_nop 0
	v_pk_mul_f32 v[86:87], v[86:87], v[104:105]
	v_lshlrev_b32_e32 v104, 16, v226
	v_and_b32_e32 v105, 0xffff0000, v226
	v_pk_mul_f32 v[104:105], v[100:101], v[104:105]
	v_lshlrev_b32_e32 v106, 16, v227
	v_and_b32_e32 v107, 0xffff0000, v227
	v_pk_fma_f32 v[104:105], v[92:93], v[126:127], v[104:105]
	v_lshlrev_b32_e32 v126, 16, v139
	v_pk_fma_f32 v[104:105], v[88:89], v[106:107], v[104:105]
	v_and_b32_e32 v127, 0xffff0000, v139
	v_pk_add_f32 v[104:105], v[96:97], v[104:105]
	s_nop 0
	v_mul_f32_e32 v106, 0xbfb8aa3b, v104
	v_mul_f32_e32 v107, 0xbfb8aa3b, v105
	v_exp_f32_e32 v106, v106
	v_exp_f32_e32 v107, v107
	v_add_f32_e32 v106, 1.0, v106
	v_add_f32_e32 v107, 1.0, v107
	v_rcp_f32_e32 v106, v106
	v_rcp_f32_e32 v107, v107
	s_nop 0
	v_pk_mul_f32 v[104:105], v[104:105], v[106:107]
	s_nop 0
	v_pk_mul_f32 v[104:105], v[80:81], v[104:105]
	v_lshlrev_b32_e32 v80, 16, v228
	v_and_b32_e32 v81, 0xffff0000, v228
	v_pk_mul_f32 v[80:81], v[102:103], v[80:81]
	v_lshlrev_b32_e32 v106, 16, v229
	v_and_b32_e32 v107, 0xffff0000, v229
	v_pk_fma_f32 v[80:81], v[94:95], v[126:127], v[80:81]
	s_nop 0
	v_pk_fma_f32 v[80:81], v[90:91], v[106:107], v[80:81]
	s_nop 0
	v_pk_add_f32 v[80:81], v[98:99], v[80:81]
	s_nop 0
	v_mul_f32_e32 v106, 0xbfb8aa3b, v80
	v_mul_f32_e32 v107, 0xbfb8aa3b, v81
	v_exp_f32_e32 v106, v106
	v_exp_f32_e32 v107, v107
	v_add_f32_e32 v106, 1.0, v106
	v_add_f32_e32 v107, 1.0, v107
	v_rcp_f32_e32 v106, v106
	v_rcp_f32_e32 v107, v107
	s_nop 0
	v_pk_mul_f32 v[80:81], v[80:81], v[106:107]
	s_nop 0
	v_pk_mul_f32 v[106:107], v[82:83], v[80:81]
	v_cvt_pk_bf16_f32 v81, v86, v87
	v_mov_b32_dpp v86, v132 row_ror:1 row_mask:0xf bank_mask:0xf
	v_cvt_pk_bf16_f32 v83, v106, v107
	v_mov_b32_dpp v107, v128 row_ror:15 row_mask:0xf bank_mask:0xf
	v_cvt_pk_bf16_f32 v80, v84, v85
	v_mad_i64_i32 v[84:85], s[0:1], v169, s26, v[172:173]
	v_cvt_pk_bf16_f32 v82, v104, v105
	v_lshl_add_u64 v[126:127], v[84:85], 0, v[204:205]
	global_store_dwordx4 v[126:127], v[80:83], off
	v_lshlrev_b32_e32 v84, 16, v132
	v_and_b32_e32 v85, 0xffff0000, v132
	v_cndmask_b32_e64 v81, v86, v140, s[4:5]
	v_lshlrev_b32_e32 v80, 16, v81
	v_and_b32_e32 v81, 0xffff0000, v81
	v_cndmask_b32_e64 v83, v170, v107, s[6:7]
	v_pk_mul_f32 v[80:81], v[120:121], v[80:81]
	v_lshlrev_b32_e32 v82, 16, v83
	v_and_b32_e32 v83, 0xffff0000, v83
	v_pk_fma_f32 v[80:81], v[112:113], v[84:85], v[80:81]
	v_mov_b32_dpp v87, v133 row_ror:1 row_mask:0xf bank_mask:0xf
	v_pk_fma_f32 v[80:81], v[108:109], v[82:83], v[80:81]
	v_cndmask_b32_e64 v140, v171, v136, s[6:7]
	v_pk_add_f32 v[80:81], v[116:117], v[80:81]
	v_lshlrev_b32_e32 v84, 16, v133
	v_mul_f32_e32 v82, 0xbfb8aa3b, v80
	v_mul_f32_e32 v83, 0xbfb8aa3b, v81
	v_exp_f32_e32 v82, v82
	v_exp_f32_e32 v83, v83
	v_cndmask_b32_e64 v139, v87, v141, s[4:5]
	v_and_b32_e32 v85, 0xffff0000, v133
	v_add_f32_e32 v82, 1.0, v82
	v_add_f32_e32 v83, 1.0, v83
	v_rcp_f32_e32 v82, v82
	v_rcp_f32_e32 v83, v83
	v_mov_b32_dpp v104, v134 row_ror:1 row_mask:0xf bank_mask:0xf
	v_mov_b32_dpp v105, v135 row_ror:1 row_mask:0xf bank_mask:0xf
	v_cndmask_b32_e64 v169, v175, v138, s[6:7]
	v_pk_mul_f32 v[80:81], v[80:81], v[82:83]
	v_lshlrev_b32_e32 v82, 16, v140
	v_pk_mul_f32 v[76:77], v[76:77], v[80:81]
	v_lshlrev_b32_e32 v80, 16, v139
	v_and_b32_e32 v81, 0xffff0000, v139
	v_pk_mul_f32 v[80:81], v[122:123], v[80:81]
	v_and_b32_e32 v83, 0xffff0000, v140
	v_pk_fma_f32 v[80:81], v[114:115], v[84:85], v[80:81]
	v_cndmask_b32_e64 v141, v104, v142, s[4:5]
	v_pk_fma_f32 v[80:81], v[110:111], v[82:83], v[80:81]
	v_cndmask_b32_e64 v142, v174, v137, s[6:7]
	v_pk_add_f32 v[80:81], v[118:119], v[80:81]
	v_lshlrev_b32_e32 v84, 16, v134
	v_mul_f32_e32 v82, 0xbfb8aa3b, v80
	v_mul_f32_e32 v83, 0xbfb8aa3b, v81
	v_exp_f32_e32 v82, v82
	v_exp_f32_e32 v83, v83
	v_and_b32_e32 v85, 0xffff0000, v134
	v_cndmask_b32_e64 v143, v105, v143, s[4:5]
	v_add_f32_e32 v82, 1.0, v82
	v_add_f32_e32 v83, 1.0, v83
	v_rcp_f32_e32 v82, v82
	v_rcp_f32_e32 v83, v83
	v_or_b32_e32 v106, 32, v164
	v_pk_mul_f32 v[80:81], v[80:81], v[82:83]
	s_nop 0
	v_pk_mul_f32 v[78:79], v[78:79], v[80:81]
	v_lshlrev_b32_e32 v80, 16, v141
	v_and_b32_e32 v81, 0xffff0000, v141
	v_pk_mul_f32 v[80:81], v[100:101], v[80:81]
	v_lshlrev_b32_e32 v82, 16, v142
	v_and_b32_e32 v83, 0xffff0000, v142
	v_pk_fma_f32 v[80:81], v[92:93], v[84:85], v[80:81]
	v_lshlrev_b32_e32 v84, 16, v135
	v_pk_fma_f32 v[80:81], v[88:89], v[82:83], v[80:81]
	v_and_b32_e32 v85, 0xffff0000, v135
	v_pk_add_f32 v[80:81], v[96:97], v[80:81]
	s_nop 0
	v_mul_f32_e32 v82, 0xbfb8aa3b, v80
	v_mul_f32_e32 v83, 0xbfb8aa3b, v81
	v_exp_f32_e32 v82, v82
	v_exp_f32_e32 v83, v83
	v_add_f32_e32 v82, 1.0, v82
	v_add_f32_e32 v83, 1.0, v83
	v_rcp_f32_e32 v82, v82
	v_rcp_f32_e32 v83, v83
	s_nop 0
	v_pk_mul_f32 v[80:81], v[80:81], v[82:83]
	s_nop 0
	v_pk_mul_f32 v[80:81], v[72:73], v[80:81]
	v_lshlrev_b32_e32 v72, 16, v143
	v_and_b32_e32 v73, 0xffff0000, v143
	v_pk_mul_f32 v[72:73], v[102:103], v[72:73]
	v_lshlrev_b32_e32 v82, 16, v169
	v_and_b32_e32 v83, 0xffff0000, v169
	v_pk_fma_f32 v[72:73], v[94:95], v[84:85], v[72:73]
	v_cndmask_b32_e64 v84, v138, v165, s[6:7]
	v_pk_fma_f32 v[72:73], v[90:91], v[82:83], v[72:73]
	s_nop 0
	v_pk_add_f32 v[72:73], v[98:99], v[72:73]
	s_nop 0
	v_mul_f32_e32 v82, 0xbfb8aa3b, v72
	v_mul_f32_e32 v83, 0xbfb8aa3b, v73
	v_exp_f32_e32 v82, v82
	v_exp_f32_e32 v83, v83
	v_add_f32_e32 v82, 1.0, v82
	v_add_f32_e32 v83, 1.0, v83
	v_rcp_f32_e32 v82, v82
	v_rcp_f32_e32 v83, v83
	s_nop 0
	v_pk_mul_f32 v[72:73], v[72:73], v[82:83]
	s_nop 0
	v_pk_mul_f32 v[82:83], v[74:75], v[72:73]
	v_cvt_pk_bf16_f32 v72, v76, v77
	v_mad_i64_i32 v[76:77], s[0:1], v106, s26, v[172:173]
	v_cvt_pk_bf16_f32 v73, v78, v79
	v_cvt_pk_bf16_f32 v74, v80, v81
	v_cvt_pk_bf16_f32 v75, v82, v83
	v_lshl_add_u64 v[132:133], v[76:77], 0, v[204:205]
	global_store_dwordx4 v[132:133], v[72:75], off
	ds_bpermute_b32 v72, v193, v128
	ds_bpermute_b32 v73, v193, v129
	v_mov_b32_dpp v74, v130 row_ror:1 row_mask:0xf bank_mask:0xf
	v_mov_b32_dpp v75, v131 row_ror:1 row_mask:0xf bank_mask:0xf
	v_cndmask_b32_e64 v77, v107, v168, s[6:7]
	s_waitcnt lgkmcnt(0)
	v_cndmask_b32_e64 v76, v72, v86, s[4:5]
	v_cndmask_b32_e64 v79, v73, v87, s[4:5]
	v_lshlrev_b32_e32 v72, 16, v76
	v_and_b32_e32 v73, 0xffff0000, v76
	v_cndmask_b32_e64 v81, v74, v104, s[4:5]
	v_cndmask_b32_e64 v83, v75, v105, s[4:5]
	v_lshlrev_b32_e32 v74, 16, v77
	v_and_b32_e32 v75, 0xffff0000, v77
	v_pk_mul_f32 v[72:73], v[120:121], v[72:73]
	v_lshlrev_b32_e32 v76, 16, v128
	v_and_b32_e32 v77, 0xffff0000, v128
	v_pk_fma_f32 v[72:73], v[112:113], v[76:77], v[72:73]
	v_cndmask_b32_e64 v80, v136, v167, s[6:7]
	v_pk_fma_f32 v[72:73], v[108:109], v[74:75], v[72:73]
	v_lshlrev_b32_e32 v76, 16, v129
	v_pk_add_f32 v[72:73], v[116:117], v[72:73]
	v_and_b32_e32 v77, 0xffff0000, v129
	v_mul_f32_e32 v74, 0xbfb8aa3b, v72
	v_mul_f32_e32 v75, 0xbfb8aa3b, v73
	v_exp_f32_e32 v74, v74
	v_exp_f32_e32 v75, v75
	v_cndmask_b32_e64 v82, v137, v166, s[6:7]
	v_or_b32_e32 v78, 48, v164
	v_add_f32_e32 v74, 1.0, v74
	v_add_f32_e32 v75, 1.0, v75
	v_rcp_f32_e32 v74, v74
	v_rcp_f32_e32 v75, v75
	s_nop 0
	v_pk_mul_f32 v[72:73], v[72:73], v[74:75]
	s_nop 0
	v_pk_mul_f32 v[68:69], v[68:69], v[72:73]
	v_lshlrev_b32_e32 v72, 16, v79
	v_and_b32_e32 v73, 0xffff0000, v79
	v_pk_mul_f32 v[72:73], v[122:123], v[72:73]
	v_lshlrev_b32_e32 v74, 16, v80
	v_and_b32_e32 v75, 0xffff0000, v80
	v_pk_fma_f32 v[72:73], v[114:115], v[76:77], v[72:73]
	v_lshlrev_b32_e32 v76, 16, v130
	v_pk_fma_f32 v[72:73], v[110:111], v[74:75], v[72:73]
	v_and_b32_e32 v77, 0xffff0000, v130
	v_pk_add_f32 v[72:73], v[118:119], v[72:73]
	s_nop 0
	v_mul_f32_e32 v74, 0xbfb8aa3b, v72
	v_mul_f32_e32 v75, 0xbfb8aa3b, v73
	v_exp_f32_e32 v74, v74
	v_exp_f32_e32 v75, v75
	v_add_f32_e32 v74, 1.0, v74
	v_add_f32_e32 v75, 1.0, v75
	v_rcp_f32_e32 v74, v74
	v_rcp_f32_e32 v75, v75
	s_nop 0
	v_pk_mul_f32 v[72:73], v[72:73], v[74:75]
	s_nop 0
	v_pk_mul_f32 v[70:71], v[70:71], v[72:73]
	v_lshlrev_b32_e32 v72, 16, v81
	v_and_b32_e32 v73, 0xffff0000, v81
	v_pk_mul_f32 v[72:73], v[100:101], v[72:73]
	v_lshlrev_b32_e32 v74, 16, v82
	v_and_b32_e32 v75, 0xffff0000, v82
	v_pk_fma_f32 v[72:73], v[92:93], v[76:77], v[72:73]
	v_lshlrev_b32_e32 v76, 16, v131
	v_pk_fma_f32 v[72:73], v[88:89], v[74:75], v[72:73]
	v_and_b32_e32 v77, 0xffff0000, v131
	v_pk_add_f32 v[72:73], v[96:97], v[72:73]
	s_nop 0
	v_mul_f32_e32 v74, 0xbfb8aa3b, v72
	v_mul_f32_e32 v75, 0xbfb8aa3b, v73
	v_exp_f32_e32 v74, v74
	v_exp_f32_e32 v75, v75
	v_add_f32_e32 v74, 1.0, v74
	v_add_f32_e32 v75, 1.0, v75
	v_rcp_f32_e32 v74, v74
	v_rcp_f32_e32 v75, v75
	s_nop 0
	v_pk_mul_f32 v[72:73], v[72:73], v[74:75]
	s_nop 0
	v_pk_mul_f32 v[72:73], v[64:65], v[72:73]
	v_lshlrev_b32_e32 v64, 16, v83
	v_and_b32_e32 v65, 0xffff0000, v83
	v_pk_mul_f32 v[64:65], v[102:103], v[64:65]
	v_lshlrev_b32_e32 v74, 16, v84
	v_and_b32_e32 v75, 0xffff0000, v84
	v_pk_fma_f32 v[64:65], v[94:95], v[76:77], v[64:65]
	s_nop 0
	v_pk_fma_f32 v[64:65], v[90:91], v[74:75], v[64:65]
	s_nop 0
	v_pk_add_f32 v[64:65], v[98:99], v[64:65]
	s_nop 0
	v_mul_f32_e32 v74, 0xbfb8aa3b, v64
	v_mul_f32_e32 v75, 0xbfb8aa3b, v65
	v_exp_f32_e32 v74, v74
	v_exp_f32_e32 v75, v75
	v_add_f32_e32 v74, 1.0, v74
	v_add_f32_e32 v75, 1.0, v75
	v_rcp_f32_e32 v74, v74
	v_rcp_f32_e32 v75, v75
	s_nop 0
	v_pk_mul_f32 v[64:65], v[64:65], v[74:75]
	s_nop 0
	v_pk_mul_f32 v[74:75], v[66:67], v[64:65]
	v_cvt_pk_bf16_f32 v64, v68, v69
	v_mad_i64_i32 v[68:69], s[0:1], v78, s26, v[172:173]
	v_cvt_pk_bf16_f32 v65, v70, v71
	v_cvt_pk_bf16_f32 v66, v72, v73
	v_cvt_pk_bf16_f32 v67, v74, v75
	v_lshl_add_u64 v[112:113], v[68:69], 0, v[204:205]
	global_store_dwordx4 v[112:113], v[64:67], off
	s_mov_b64 s[0:1], -1
	s_nop 0
	v_or_b32_e32 v64, 0x80, v192
	v_ashrrev_i32_e32 v65, 31, v64
	v_lshlrev_b64 v[64:65], 2, v[64:65]
	v_lshl_add_u64 v[66:67], s[46:47], 0, v[64:65]
	v_lshl_add_u64 v[72:73], s[48:49], 0, v[64:65]
	global_load_dwordx4 v[76:79], v[190:191], off offset:528
	global_load_dwordx4 v[92:95], v[190:191], off offset:512
	global_load_dwordx4 v[68:71], v[66:67], off offset:16
	global_load_dwordx4 v[84:87], v[66:67], off
	s_nop 0
	global_load_dwordx4 v[64:67], v[72:73], off offset:16
	global_load_dwordx4 v[80:83], v[72:73], off
	s_nop 0
	global_load_dwordx4 v[72:75], v[188:189], off offset:528
	global_load_dwordx4 v[88:91], v[188:189], off offset:512
	global_load_dwordx4 v[108:111], v[194:195], off offset:256
	global_load_dwordx4 v[104:107], v[198:199], off offset:256
	global_load_dwordx4 v[100:103], v[200:201], off offset:256
	global_load_dwordx4 v[96:99], v[206:207], off offset:256
	global_load_dwordx4 v[114:117], v[196:197], off offset:256
	global_load_dwordx4 v[118:121], v[202:203], off offset:256
	s_waitcnt vmcnt(5)
	v_mov_b32_dpp v130, v108 row_ror:1 row_mask:0xf bank_mask:0xf
	s_waitcnt vmcnt(4)
	v_mov_b32_dpp v136, v104 row_ror:15 row_mask:0xf bank_mask:0xf
	v_mov_b32_dpp v137, v105 row_ror:15 row_mask:0xf bank_mask:0xf
	v_mov_b32_dpp v134, v110 row_ror:1 row_mask:0xf bank_mask:0xf
	s_waitcnt vmcnt(1)
	v_cndmask_b32_e64 v122, v117, 0, s[62:63]
	v_cndmask_b32_e64 v123, v116, 0, s[62:63]
	s_waitcnt vmcnt(0)
	v_cndmask_b32_e64 v116, v119, 0, s[50:51]
	v_cndmask_b32_e64 v117, v118, 0, s[50:51]
	v_mov_b32_dpp v118, v108 row_ror:15 row_mask:0xf bank_mask:0xf
	v_mov_b32_dpp v119, v109 row_ror:15 row_mask:0xf bank_mask:0xf
	v_mov_b32_dpp v135, v111 row_ror:1 row_mask:0xf bank_mask:0xf
	v_cndmask_b32_e64 v128, v115, 0, s[62:63]
	v_cndmask_b32_e64 v129, v114, 0, s[62:63]
	v_cndmask_b32_e64 v114, v121, 0, s[50:51]
	v_cndmask_b32_e64 v115, v120, 0, s[50:51]
	v_mov_b32_dpp v120, v110 row_ror:15 row_mask:0xf bank_mask:0xf
	v_mov_b32_dpp v121, v111 row_ror:15 row_mask:0xf bank_mask:0xf
	v_mov_b32_dpp v138, v106 row_ror:15 row_mask:0xf bank_mask:0xf
	v_mov_b32_dpp v139, v107 row_ror:15 row_mask:0xf bank_mask:0xf
	v_cndmask_b32_e64 v129, v130, v129, s[4:5]
	v_cndmask_b32_e64 v140, v118, v136, s[6:7]
	v_cndmask_b32_e64 v141, v119, v137, s[6:7]
	v_lshlrev_b32_e32 v118, 16, v129
	v_and_b32_e32 v119, 0xffff0000, v129
	v_cndmask_b32_e64 v142, v134, v123, s[4:5]
	v_cndmask_b32_e64 v164, v135, v122, s[4:5]
	v_pk_mul_f32 v[118:119], v[92:93], v[118:119]
	v_lshlrev_b32_e32 v122, 16, v108
	v_and_b32_e32 v123, 0xffff0000, v108
	v_cndmask_b32_e64 v143, v120, v138, s[6:7]
	v_cndmask_b32_e64 v165, v121, v139, s[6:7]
	v_lshlrev_b32_e32 v120, 16, v140
	v_and_b32_e32 v121, 0xffff0000, v140
	v_pk_fma_f32 v[118:119], v[84:85], v[122:123], v[118:119]
	v_mov_b32_dpp v131, v109 row_ror:1 row_mask:0xf bank_mask:0xf
	v_pk_fma_f32 v[118:119], v[80:81], v[120:121], v[118:119]
	v_cndmask_b32_e64 v128, v131, v128, s[4:5]
	v_pk_add_f32 v[118:119], v[88:89], v[118:119]
	s_nop 0
	v_mul_f32_e32 v108, 0xbfb8aa3b, v118
	v_exp_f32_e32 v108, v108
	s_nop 0
	v_add_f32_e32 v108, 1.0, v108
	v_rcp_f32_e32 v120, v108
	v_mul_f32_e32 v108, 0xbfb8aa3b, v119
	v_exp_f32_e32 v108, v108
	s_nop 0
	v_add_f32_e32 v108, 1.0, v108
	v_rcp_f32_e32 v121, v108
	v_lshlrev_b32_e32 v108, 16, v109
	v_and_b32_e32 v109, 0xffff0000, v109
	v_pk_mul_f32 v[118:119], v[118:119], v[120:121]
	s_nop 0
	v_pk_mul_f32 v[60:61], v[60:61], v[118:119]
	v_lshlrev_b32_e32 v118, 16, v128
	v_and_b32_e32 v119, 0xffff0000, v128
	v_pk_mul_f32 v[118:119], v[94:95], v[118:119]
	v_lshlrev_b32_e32 v120, 16, v141
	v_and_b32_e32 v121, 0xffff0000, v141
	v_pk_fma_f32 v[108:109], v[86:87], v[108:109], v[118:119]
	s_nop 0
	v_pk_fma_f32 v[108:109], v[82:83], v[120:121], v[108:109]
	v_lshlrev_b32_e32 v120, 16, v110
	v_pk_add_f32 v[108:109], v[90:91], v[108:109]
	v_and_b32_e32 v121, 0xffff0000, v110
	v_mul_f32_e32 v118, 0xbfb8aa3b, v108
	v_mul_f32_e32 v119, 0xbfb8aa3b, v109
	v_exp_f32_e32 v118, v118
	v_exp_f32_e32 v119, v119
	v_add_f32_e32 v118, 1.0, v118
	v_add_f32_e32 v119, 1.0, v119
	v_rcp_f32_e32 v118, v118
	v_rcp_f32_e32 v119, v119
	s_nop 0
	v_pk_mul_f32 v[108:109], v[108:109], v[118:119]
	s_nop 0
	v_pk_mul_f32 v[62:63], v[62:63], v[108:109]
	v_lshlrev_b32_e32 v108, 16, v142
	v_and_b32_e32 v109, 0xffff0000, v142
	v_pk_mul_f32 v[108:109], v[76:77], v[108:109]
	v_lshlrev_b32_e32 v118, 16, v143
	v_and_b32_e32 v119, 0xffff0000, v143
	v_pk_fma_f32 v[108:109], v[68:69], v[120:121], v[108:109]
	s_nop 0
	v_pk_fma_f32 v[108:109], v[64:65], v[118:119], v[108:109]
	s_nop 0
	v_pk_add_f32 v[108:109], v[72:73], v[108:109]
	s_nop 0
	v_mul_f32_e32 v110, 0xbfb8aa3b, v108
	v_exp_f32_e32 v110, v110
	s_nop 0
	v_add_f32_e32 v110, 1.0, v110
	v_rcp_f32_e32 v118, v110
	v_mul_f32_e32 v110, 0xbfb8aa3b, v109
	v_exp_f32_e32 v110, v110
	s_nop 0
	v_add_f32_e32 v110, 1.0, v110
	v_rcp_f32_e32 v119, v110
	v_lshlrev_b32_e32 v110, 16, v111
	v_and_b32_e32 v111, 0xffff0000, v111
	v_pk_mul_f32 v[108:109], v[108:109], v[118:119]
	s_nop 0
	v_pk_mul_f32 v[108:109], v[56:57], v[108:109]
	v_lshlrev_b32_e32 v56, 16, v164
	v_and_b32_e32 v57, 0xffff0000, v164
	v_pk_mul_f32 v[56:57], v[78:79], v[56:57]
	v_lshlrev_b32_e32 v118, 16, v165
	v_and_b32_e32 v119, 0xffff0000, v165
	v_pk_fma_f32 v[56:57], v[70:71], v[110:111], v[56:57]
	s_nop 0
	v_pk_fma_f32 v[56:57], v[66:67], v[118:119], v[56:57]
	v_mov_b32_dpp v118, v102 row_ror:15 row_mask:0xf bank_mask:0xf
	v_pk_add_f32 v[56:57], v[74:75], v[56:57]
	v_mov_b32_dpp v119, v103 row_ror:15 row_mask:0xf bank_mask:0xf
	v_mul_f32_e32 v110, 0xbfb8aa3b, v56
	v_mul_f32_e32 v111, 0xbfb8aa3b, v57
	v_exp_f32_e32 v110, v110
	v_exp_f32_e32 v111, v111
	v_cndmask_b32_e64 v123, v138, v118, s[6:7]
	v_cndmask_b32_e64 v129, v139, v119, s[6:7]
	v_add_f32_e32 v110, 1.0, v110
	v_add_f32_e32 v111, 1.0, v111
	v_rcp_f32_e32 v110, v110
	v_rcp_f32_e32 v111, v111
	s_nop 0
	v_pk_mul_f32 v[56:57], v[56:57], v[110:111]
	s_nop 0
	v_pk_mul_f32 v[110:111], v[58:59], v[56:57]
	v_cvt_pk_bf16_f32 v57, v62, v63
	v_mov_b32_dpp v62, v104 row_ror:1 row_mask:0xf bank_mask:0xf
	v_cvt_pk_bf16_f32 v59, v110, v111
	v_mov_b32_dpp v110, v100 row_ror:15 row_mask:0xf bank_mask:0xf
	v_cvt_pk_bf16_f32 v56, v60, v61
	v_cvt_pk_bf16_f32 v58, v108, v109
	global_store_dwordx4 v[156:157], v[56:59], off offset:256
	v_lshlrev_b32_e32 v60, 16, v104
	v_and_b32_e32 v61, 0xffff0000, v104
	v_cndmask_b32_e64 v57, v62, v130, s[4:5]
	v_lshlrev_b32_e32 v56, 16, v57
	v_and_b32_e32 v57, 0xffff0000, v57
	v_cndmask_b32_e64 v59, v136, v110, s[6:7]
	v_pk_mul_f32 v[56:57], v[92:93], v[56:57]
	v_lshlrev_b32_e32 v58, 16, v59
	v_and_b32_e32 v59, 0xffff0000, v59
	v_pk_fma_f32 v[56:57], v[84:85], v[60:61], v[56:57]
	v_mov_b32_dpp v63, v105 row_ror:1 row_mask:0xf bank_mask:0xf
	v_pk_fma_f32 v[56:57], v[80:81], v[58:59], v[56:57]
	v_mov_b32_dpp v111, v101 row_ror:15 row_mask:0xf bank_mask:0xf
	v_pk_add_f32 v[56:57], v[88:89], v[56:57]
	v_lshlrev_b32_e32 v60, 16, v105
	v_mul_f32_e32 v58, 0xbfb8aa3b, v56
	v_mul_f32_e32 v59, 0xbfb8aa3b, v57
	v_exp_f32_e32 v58, v58
	v_exp_f32_e32 v59, v59
	v_cndmask_b32_e64 v120, v63, v131, s[4:5]
	v_cndmask_b32_e64 v121, v137, v111, s[6:7]
	v_add_f32_e32 v58, 1.0, v58
	v_add_f32_e32 v59, 1.0, v59
	v_rcp_f32_e32 v58, v58
	v_rcp_f32_e32 v59, v59
	v_and_b32_e32 v61, 0xffff0000, v105
	v_mov_b32_dpp v108, v106 row_ror:1 row_mask:0xf bank_mask:0xf
	v_mov_b32_dpp v109, v107 row_ror:1 row_mask:0xf bank_mask:0xf
	v_pk_mul_f32 v[56:57], v[56:57], v[58:59]
	v_lshlrev_b32_e32 v58, 16, v121
	v_pk_mul_f32 v[52:53], v[52:53], v[56:57]
	v_lshlrev_b32_e32 v56, 16, v120
	v_and_b32_e32 v57, 0xffff0000, v120
	v_pk_mul_f32 v[56:57], v[94:95], v[56:57]
	v_and_b32_e32 v59, 0xffff0000, v121
	v_pk_fma_f32 v[56:57], v[86:87], v[60:61], v[56:57]
	v_cndmask_b32_e64 v122, v108, v134, s[4:5]
	v_pk_fma_f32 v[56:57], v[82:83], v[58:59], v[56:57]
	v_lshlrev_b32_e32 v60, 16, v106
	v_pk_add_f32 v[56:57], v[90:91], v[56:57]
	v_and_b32_e32 v61, 0xffff0000, v106
	v_mul_f32_e32 v58, 0xbfb8aa3b, v56
	v_mul_f32_e32 v59, 0xbfb8aa3b, v57
	v_exp_f32_e32 v58, v58
	v_exp_f32_e32 v59, v59
	v_cndmask_b32_e64 v128, v109, v135, s[4:5]
	v_add_f32_e32 v58, 1.0, v58
	v_add_f32_e32 v59, 1.0, v59
	v_rcp_f32_e32 v58, v58
	v_rcp_f32_e32 v59, v59
	s_nop 0
	v_pk_mul_f32 v[56:57], v[56:57], v[58:59]
	s_nop 0
	v_pk_mul_f32 v[54:55], v[54:55], v[56:57]
	v_lshlrev_b32_e32 v56, 16, v122
	v_and_b32_e32 v57, 0xffff0000, v122
	v_pk_mul_f32 v[56:57], v[76:77], v[56:57]
	v_lshlrev_b32_e32 v58, 16, v123
	v_and_b32_e32 v59, 0xffff0000, v123
	v_pk_fma_f32 v[56:57], v[68:69], v[60:61], v[56:57]
	v_lshlrev_b32_e32 v60, 16, v107
	v_pk_fma_f32 v[56:57], v[64:65], v[58:59], v[56:57]
	v_and_b32_e32 v61, 0xffff0000, v107
	v_pk_add_f32 v[56:57], v[72:73], v[56:57]
	s_nop 0
	v_mul_f32_e32 v58, 0xbfb8aa3b, v56
	v_mul_f32_e32 v59, 0xbfb8aa3b, v57
	v_exp_f32_e32 v58, v58
	v_exp_f32_e32 v59, v59
	v_add_f32_e32 v58, 1.0, v58
	v_add_f32_e32 v59, 1.0, v59
	v_rcp_f32_e32 v58, v58
	v_rcp_f32_e32 v59, v59
	s_nop 0
	v_pk_mul_f32 v[56:57], v[56:57], v[58:59]
	s_nop 0
	v_pk_mul_f32 v[56:57], v[48:49], v[56:57]
	v_lshlrev_b32_e32 v48, 16, v128
	v_and_b32_e32 v49, 0xffff0000, v128
	v_pk_mul_f32 v[48:49], v[78:79], v[48:49]
	v_lshlrev_b32_e32 v58, 16, v129
	v_and_b32_e32 v59, 0xffff0000, v129
	v_pk_fma_f32 v[48:49], v[70:71], v[60:61], v[48:49]
	v_mov_b32_dpp v60, v98 row_ror:15 row_mask:0xf bank_mask:0xf
	v_pk_fma_f32 v[48:49], v[66:67], v[58:59], v[48:49]
	v_mov_b32_dpp v61, v99 row_ror:15 row_mask:0xf bank_mask:0xf
	v_pk_add_f32 v[48:49], v[74:75], v[48:49]
	v_cndmask_b32_e64 v105, v118, v60, s[6:7]
	v_mul_f32_e32 v58, 0xbfb8aa3b, v48
	v_mul_f32_e32 v59, 0xbfb8aa3b, v49
	v_exp_f32_e32 v58, v58
	v_exp_f32_e32 v59, v59
	v_cndmask_b32_e64 v107, v119, v61, s[6:7]
	v_add_f32_e32 v58, 1.0, v58
	v_add_f32_e32 v59, 1.0, v59
	v_rcp_f32_e32 v58, v58
	v_rcp_f32_e32 v59, v59
	s_nop 0
	v_pk_mul_f32 v[48:49], v[48:49], v[58:59]
	s_nop 0
	v_pk_mul_f32 v[58:59], v[50:51], v[48:49]
	v_cvt_pk_bf16_f32 v49, v54, v55
	v_mov_b32_dpp v54, v100 row_ror:1 row_mask:0xf bank_mask:0xf
	v_cvt_pk_bf16_f32 v51, v58, v59
	v_mov_b32_dpp v58, v96 row_ror:15 row_mask:0xf bank_mask:0xf
	v_cvt_pk_bf16_f32 v48, v52, v53
	v_cvt_pk_bf16_f32 v50, v56, v57
	global_store_dwordx4 v[146:147], v[48:51], off offset:256
	v_lshlrev_b32_e32 v52, 16, v100
	v_and_b32_e32 v53, 0xffff0000, v100
	v_cndmask_b32_e64 v49, v54, v62, s[4:5]
	v_lshlrev_b32_e32 v48, 16, v49
	v_and_b32_e32 v49, 0xffff0000, v49
	v_cndmask_b32_e64 v51, v110, v58, s[6:7]
	v_pk_mul_f32 v[48:49], v[92:93], v[48:49]
	v_lshlrev_b32_e32 v50, 16, v51
	v_and_b32_e32 v51, 0xffff0000, v51
	v_pk_fma_f32 v[48:49], v[84:85], v[52:53], v[48:49]
	v_mov_b32_dpp v55, v101 row_ror:1 row_mask:0xf bank_mask:0xf
	v_pk_fma_f32 v[48:49], v[80:81], v[50:51], v[48:49]
	v_mov_b32_dpp v59, v97 row_ror:15 row_mask:0xf bank_mask:0xf
	v_pk_add_f32 v[48:49], v[88:89], v[48:49]
	v_lshlrev_b32_e32 v52, 16, v101
	v_mul_f32_e32 v50, 0xbfb8aa3b, v48
	v_mul_f32_e32 v51, 0xbfb8aa3b, v49
	v_exp_f32_e32 v50, v50
	v_exp_f32_e32 v51, v51
	v_cndmask_b32_e64 v62, v55, v63, s[4:5]
	v_cndmask_b32_e64 v63, v111, v59, s[6:7]
	v_add_f32_e32 v50, 1.0, v50
	v_add_f32_e32 v51, 1.0, v51
	v_rcp_f32_e32 v50, v50
	v_rcp_f32_e32 v51, v51
	v_and_b32_e32 v53, 0xffff0000, v101
	v_mov_b32_dpp v56, v102 row_ror:1 row_mask:0xf bank_mask:0xf
	v_mov_b32_dpp v57, v103 row_ror:1 row_mask:0xf bank_mask:0xf
	v_pk_mul_f32 v[48:49], v[48:49], v[50:51]
	v_lshlrev_b32_e32 v50, 16, v63
	v_pk_mul_f32 v[44:45], v[44:45], v[48:49]
	v_lshlrev_b32_e32 v48, 16, v62
	v_and_b32_e32 v49, 0xffff0000, v62
	v_pk_mul_f32 v[48:49], v[94:95], v[48:49]
	v_and_b32_e32 v51, 0xffff0000, v63
	v_pk_fma_f32 v[48:49], v[86:87], v[52:53], v[48:49]
	v_cndmask_b32_e64 v104, v56, v108, s[4:5]
	v_pk_fma_f32 v[48:49], v[82:83], v[50:51], v[48:49]
	v_lshlrev_b32_e32 v52, 16, v102
	v_pk_add_f32 v[48:49], v[90:91], v[48:49]
	v_and_b32_e32 v53, 0xffff0000, v102
	v_mul_f32_e32 v50, 0xbfb8aa3b, v48
	v_mul_f32_e32 v51, 0xbfb8aa3b, v49
	v_exp_f32_e32 v50, v50
	v_exp_f32_e32 v51, v51
	v_cndmask_b32_e64 v106, v57, v109, s[4:5]
	v_add_f32_e32 v50, 1.0, v50
	v_add_f32_e32 v51, 1.0, v51
	v_rcp_f32_e32 v50, v50
	v_rcp_f32_e32 v51, v51
	s_nop 0
	v_pk_mul_f32 v[48:49], v[48:49], v[50:51]
	s_nop 0
	v_pk_mul_f32 v[46:47], v[46:47], v[48:49]
	v_lshlrev_b32_e32 v48, 16, v104
	v_and_b32_e32 v49, 0xffff0000, v104
	v_pk_mul_f32 v[48:49], v[76:77], v[48:49]
	v_lshlrev_b32_e32 v50, 16, v105
	v_and_b32_e32 v51, 0xffff0000, v105
	v_pk_fma_f32 v[48:49], v[68:69], v[52:53], v[48:49]
	v_lshlrev_b32_e32 v52, 16, v103
	v_pk_fma_f32 v[48:49], v[64:65], v[50:51], v[48:49]
	v_and_b32_e32 v53, 0xffff0000, v103
	v_pk_add_f32 v[48:49], v[72:73], v[48:49]
	s_nop 0
	v_mul_f32_e32 v50, 0xbfb8aa3b, v48
	v_mul_f32_e32 v51, 0xbfb8aa3b, v49
	v_exp_f32_e32 v50, v50
	v_exp_f32_e32 v51, v51
	v_add_f32_e32 v50, 1.0, v50
	v_add_f32_e32 v51, 1.0, v51
	v_rcp_f32_e32 v50, v50
	v_rcp_f32_e32 v51, v51
	s_nop 0
	v_pk_mul_f32 v[48:49], v[48:49], v[50:51]
	s_nop 0
	v_pk_mul_f32 v[48:49], v[40:41], v[48:49]
	v_lshlrev_b32_e32 v40, 16, v106
	v_and_b32_e32 v41, 0xffff0000, v106
	v_pk_mul_f32 v[40:41], v[78:79], v[40:41]
	v_lshlrev_b32_e32 v50, 16, v107
	v_and_b32_e32 v51, 0xffff0000, v107
	v_pk_fma_f32 v[40:41], v[70:71], v[52:53], v[40:41]
	s_nop 0
	v_pk_fma_f32 v[40:41], v[66:67], v[50:51], v[40:41]
	s_nop 0
	v_pk_add_f32 v[40:41], v[74:75], v[40:41]
	s_nop 0
	v_mul_f32_e32 v50, 0xbfb8aa3b, v40
	v_mul_f32_e32 v51, 0xbfb8aa3b, v41
	v_exp_f32_e32 v50, v50
	v_exp_f32_e32 v51, v51
	v_add_f32_e32 v50, 1.0, v50
	v_add_f32_e32 v51, 1.0, v51
	v_rcp_f32_e32 v50, v50
	v_rcp_f32_e32 v51, v51
	s_nop 0
	v_pk_mul_f32 v[40:41], v[40:41], v[50:51]
	s_nop 0
	v_pk_mul_f32 v[50:51], v[42:43], v[40:41]
	v_cvt_pk_bf16_f32 v40, v44, v45
	v_cvt_pk_bf16_f32 v41, v46, v47
	v_cvt_pk_bf16_f32 v42, v48, v49
	v_cvt_pk_bf16_f32 v43, v50, v51
	global_store_dwordx4 v[148:149], v[40:43], off offset:256
	ds_bpermute_b32 v40, v193, v96
	ds_bpermute_b32 v41, v193, v97
	v_mov_b32_dpp v42, v98 row_ror:1 row_mask:0xf bank_mask:0xf
	v_mov_b32_dpp v43, v99 row_ror:1 row_mask:0xf bank_mask:0xf
	v_cndmask_b32_e64 v45, v58, v117, s[6:7]
	s_waitcnt lgkmcnt(0)
	v_cndmask_b32_e64 v44, v40, v54, s[4:5]
	v_cndmask_b32_e64 v46, v41, v55, s[4:5]
	v_lshlrev_b32_e32 v40, 16, v44
	v_and_b32_e32 v41, 0xffff0000, v44
	v_cndmask_b32_e64 v48, v42, v56, s[4:5]
	v_cndmask_b32_e64 v50, v43, v57, s[4:5]
	v_lshlrev_b32_e32 v42, 16, v45
	v_and_b32_e32 v43, 0xffff0000, v45
	v_pk_mul_f32 v[40:41], v[92:93], v[40:41]
	v_lshlrev_b32_e32 v44, 16, v96
	v_and_b32_e32 v45, 0xffff0000, v96
	v_pk_fma_f32 v[40:41], v[84:85], v[44:45], v[40:41]
	v_cndmask_b32_e64 v47, v59, v116, s[6:7]
	v_pk_fma_f32 v[40:41], v[80:81], v[42:43], v[40:41]
	v_lshlrev_b32_e32 v44, 16, v97
	v_pk_add_f32 v[40:41], v[88:89], v[40:41]
	v_and_b32_e32 v45, 0xffff0000, v97
	v_mul_f32_e32 v42, 0xbfb8aa3b, v40
	v_mul_f32_e32 v43, 0xbfb8aa3b, v41
	v_exp_f32_e32 v42, v42
	v_exp_f32_e32 v43, v43
	v_cndmask_b32_e64 v49, v60, v115, s[6:7]
	v_cndmask_b32_e64 v51, v61, v114, s[6:7]
	v_add_f32_e32 v42, 1.0, v42
	v_add_f32_e32 v43, 1.0, v43
	v_rcp_f32_e32 v42, v42
	v_rcp_f32_e32 v43, v43
	s_nop 0
	v_pk_mul_f32 v[40:41], v[40:41], v[42:43]
	s_nop 0
	v_pk_mul_f32 v[36:37], v[36:37], v[40:41]
	v_lshlrev_b32_e32 v40, 16, v46
	v_and_b32_e32 v41, 0xffff0000, v46
	v_pk_mul_f32 v[40:41], v[94:95], v[40:41]
	v_lshlrev_b32_e32 v42, 16, v47
	v_and_b32_e32 v43, 0xffff0000, v47
	v_pk_fma_f32 v[40:41], v[86:87], v[44:45], v[40:41]
	v_lshlrev_b32_e32 v44, 16, v98
	v_pk_fma_f32 v[40:41], v[82:83], v[42:43], v[40:41]
	v_and_b32_e32 v45, 0xffff0000, v98
	v_pk_add_f32 v[40:41], v[90:91], v[40:41]
	s_nop 0
	v_mul_f32_e32 v42, 0xbfb8aa3b, v40
	v_mul_f32_e32 v43, 0xbfb8aa3b, v41
	v_exp_f32_e32 v42, v42
	v_exp_f32_e32 v43, v43
	v_add_f32_e32 v42, 1.0, v42
	v_add_f32_e32 v43, 1.0, v43
	v_rcp_f32_e32 v42, v42
	v_rcp_f32_e32 v43, v43
	s_nop 0
	v_pk_mul_f32 v[40:41], v[40:41], v[42:43]
	s_nop 0
	v_pk_mul_f32 v[38:39], v[38:39], v[40:41]
	v_lshlrev_b32_e32 v40, 16, v48
	v_and_b32_e32 v41, 0xffff0000, v48
	v_pk_mul_f32 v[40:41], v[76:77], v[40:41]
	v_lshlrev_b32_e32 v42, 16, v49
	v_and_b32_e32 v43, 0xffff0000, v49
	v_pk_fma_f32 v[40:41], v[68:69], v[44:45], v[40:41]
	v_lshlrev_b32_e32 v44, 16, v99
	v_pk_fma_f32 v[40:41], v[64:65], v[42:43], v[40:41]
	v_and_b32_e32 v45, 0xffff0000, v99
	v_pk_add_f32 v[40:41], v[72:73], v[40:41]
	s_nop 0
	v_mul_f32_e32 v42, 0xbfb8aa3b, v40
	v_mul_f32_e32 v43, 0xbfb8aa3b, v41
	v_exp_f32_e32 v42, v42
	v_exp_f32_e32 v43, v43
	v_add_f32_e32 v42, 1.0, v42
	v_add_f32_e32 v43, 1.0, v43
	v_rcp_f32_e32 v42, v42
	v_rcp_f32_e32 v43, v43
	s_nop 0
	v_pk_mul_f32 v[40:41], v[40:41], v[42:43]
	s_nop 0
	v_pk_mul_f32 v[40:41], v[32:33], v[40:41]
	v_lshlrev_b32_e32 v32, 16, v50
	v_and_b32_e32 v33, 0xffff0000, v50
	v_pk_mul_f32 v[32:33], v[78:79], v[32:33]
	v_lshlrev_b32_e32 v42, 16, v51
	v_and_b32_e32 v43, 0xffff0000, v51
	v_pk_fma_f32 v[32:33], v[70:71], v[44:45], v[32:33]
	s_nop 0
	v_pk_fma_f32 v[32:33], v[66:67], v[42:43], v[32:33]
	s_nop 0
	v_pk_add_f32 v[32:33], v[74:75], v[32:33]
	s_nop 0
	v_mul_f32_e32 v42, 0xbfb8aa3b, v32
	v_mul_f32_e32 v43, 0xbfb8aa3b, v33
	v_exp_f32_e32 v42, v42
	v_exp_f32_e32 v43, v43
	v_add_f32_e32 v42, 1.0, v42
	v_add_f32_e32 v43, 1.0, v43
	v_rcp_f32_e32 v42, v42
	v_rcp_f32_e32 v43, v43
	s_nop 0
	v_pk_mul_f32 v[32:33], v[32:33], v[42:43]
	s_nop 0
	v_pk_mul_f32 v[42:43], v[34:35], v[32:33]
	v_cvt_pk_bf16_f32 v32, v36, v37
	v_cvt_pk_bf16_f32 v33, v38, v39
	v_cvt_pk_bf16_f32 v34, v40, v41
	v_cvt_pk_bf16_f32 v35, v42, v43
	global_store_dwordx4 v[144:145], v[32:35], off offset:256
	global_load_dwordx4 v[48:51], v[150:151], off offset:256
	global_load_dwordx4 v[44:47], v[152:153], off offset:256
	global_load_dwordx4 v[40:43], v[154:155], off offset:256
	global_load_dwordx4 v[32:35], v[158:159], off offset:256
	global_load_dwordx4 v[52:55], v[162:163], off offset:256
	global_load_dwordx4 v[36:39], v[160:161], off offset:256
	s_waitcnt vmcnt(5)
	v_mov_b32_dpp v58, v48 row_ror:1 row_mask:0xf bank_mask:0xf
	v_mov_b32_dpp v56, v48 row_ror:15 row_mask:0xf bank_mask:0xf
	v_mov_b32_dpp v59, v49 row_ror:1 row_mask:0xf bank_mask:0xf
	s_waitcnt vmcnt(4)
	v_mov_b32_dpp v96, v44 row_ror:15 row_mask:0xf bank_mask:0xf
	v_mov_b32_dpp v57, v49 row_ror:15 row_mask:0xf bank_mask:0xf
	v_mov_b32_dpp v60, v50 row_ror:1 row_mask:0xf bank_mask:0xf
	v_mov_b32_dpp v62, v51 row_ror:1 row_mask:0xf bank_mask:0xf
	v_mov_b32_dpp v97, v45 row_ror:15 row_mask:0xf bank_mask:0xf
	s_waitcnt vmcnt(1)
	v_cndmask_b32_e64 v52, v52, 0, s[22:23]
	v_cndmask_b32_e64 v53, v53, 0, s[22:23]
	v_cndmask_b32_e64 v100, v58, v52, s[4:5]
	v_cndmask_b32_e64 v55, v55, 0, s[22:23]
	v_cndmask_b32_e64 v54, v54, 0, s[22:23]
	v_cndmask_b32_e64 v56, v56, v96, s[6:7]
	v_cndmask_b32_e64 v101, v59, v53, s[4:5]
	v_lshlrev_b32_e32 v52, 16, v100
	v_and_b32_e32 v53, 0xffff0000, v100
	v_cndmask_b32_e64 v102, v57, v97, s[6:7]
	v_cndmask_b32_e64 v103, v60, v54, s[4:5]
	v_cndmask_b32_e64 v104, v62, v55, s[4:5]
	v_lshlrev_b32_e32 v54, 16, v56
	v_and_b32_e32 v55, 0xffff0000, v56
	v_pk_mul_f32 v[52:53], v[92:93], v[52:53]
	v_lshlrev_b32_e32 v56, 16, v48
	v_and_b32_e32 v57, 0xffff0000, v48
	v_pk_fma_f32 v[52:53], v[84:85], v[56:57], v[52:53]
	v_mov_b32_dpp v61, v50 row_ror:15 row_mask:0xf bank_mask:0xf
	v_pk_fma_f32 v[52:53], v[80:81], v[54:55], v[52:53]
	v_mov_b32_dpp v98, v46 row_ror:15 row_mask:0xf bank_mask:0xf
	v_pk_add_f32 v[52:53], v[88:89], v[52:53]
	v_mov_b32_dpp v63, v51 row_ror:15 row_mask:0xf bank_mask:0xf
	v_mul_f32_e32 v48, 0xbfb8aa3b, v52
	v_exp_f32_e32 v48, v48
	v_cndmask_b32_e64 v61, v61, v98, s[6:7]
	v_mov_b32_dpp v99, v47 row_ror:15 row_mask:0xf bank_mask:0xf
	v_add_f32_e32 v48, 1.0, v48
	v_rcp_f32_e32 v54, v48
	v_mul_f32_e32 v48, 0xbfb8aa3b, v53
	v_exp_f32_e32 v48, v48
	v_cndmask_b32_e64 v63, v63, v99, s[6:7]
	v_add_f32_e32 v48, 1.0, v48
	v_rcp_f32_e32 v55, v48
	v_lshlrev_b32_e32 v48, 16, v49
	v_and_b32_e32 v49, 0xffff0000, v49
	v_pk_mul_f32 v[52:53], v[52:53], v[54:55]
	s_nop 0
	v_pk_mul_f32 v[28:29], v[28:29], v[52:53]
	v_lshlrev_b32_e32 v52, 16, v101
	v_and_b32_e32 v53, 0xffff0000, v101
	v_pk_mul_f32 v[52:53], v[94:95], v[52:53]
	v_lshlrev_b32_e32 v54, 16, v102
	v_and_b32_e32 v55, 0xffff0000, v102
	v_pk_fma_f32 v[48:49], v[86:87], v[48:49], v[52:53]
	s_nop 0
	v_pk_fma_f32 v[48:49], v[82:83], v[54:55], v[48:49]
	v_lshlrev_b32_e32 v54, 16, v50
	v_pk_add_f32 v[48:49], v[90:91], v[48:49]
	v_and_b32_e32 v55, 0xffff0000, v50
	v_mul_f32_e32 v52, 0xbfb8aa3b, v48
	v_mul_f32_e32 v53, 0xbfb8aa3b, v49
	v_exp_f32_e32 v52, v52
	v_exp_f32_e32 v53, v53
	v_add_f32_e32 v52, 1.0, v52
	v_add_f32_e32 v53, 1.0, v53
	v_rcp_f32_e32 v52, v52
	v_rcp_f32_e32 v53, v53
	s_nop 0
	v_pk_mul_f32 v[48:49], v[48:49], v[52:53]
	s_nop 0
	v_pk_mul_f32 v[30:31], v[30:31], v[48:49]
	v_lshlrev_b32_e32 v48, 16, v103
	v_and_b32_e32 v49, 0xffff0000, v103
	v_pk_mul_f32 v[48:49], v[76:77], v[48:49]
	v_lshlrev_b32_e32 v52, 16, v61
	v_and_b32_e32 v53, 0xffff0000, v61
	v_pk_fma_f32 v[48:49], v[68:69], v[54:55], v[48:49]
	s_nop 0
	v_pk_fma_f32 v[48:49], v[64:65], v[52:53], v[48:49]
	s_nop 0
	v_pk_add_f32 v[48:49], v[72:73], v[48:49]
	s_nop 0
	v_mul_f32_e32 v50, 0xbfb8aa3b, v48
	v_exp_f32_e32 v50, v50
	s_nop 0
	v_add_f32_e32 v50, 1.0, v50
	v_rcp_f32_e32 v52, v50
	v_mul_f32_e32 v50, 0xbfb8aa3b, v49
	v_exp_f32_e32 v50, v50
	s_nop 0
	v_add_f32_e32 v50, 1.0, v50
	v_rcp_f32_e32 v53, v50
	v_lshlrev_b32_e32 v50, 16, v51
	v_and_b32_e32 v51, 0xffff0000, v51
	v_pk_mul_f32 v[48:49], v[48:49], v[52:53]
	s_nop 0
	v_pk_mul_f32 v[48:49], v[24:25], v[48:49]
	v_lshlrev_b32_e32 v24, 16, v104
	v_and_b32_e32 v25, 0xffff0000, v104
	v_pk_mul_f32 v[24:25], v[78:79], v[24:25]
	v_lshlrev_b32_e32 v52, 16, v63
	v_and_b32_e32 v53, 0xffff0000, v63
	v_pk_fma_f32 v[24:25], v[70:71], v[50:51], v[24:25]
	s_nop 0
	v_pk_fma_f32 v[24:25], v[66:67], v[52:53], v[24:25]
	v_mov_b32_dpp v52, v42 row_ror:15 row_mask:0xf bank_mask:0xf
	v_pk_add_f32 v[24:25], v[74:75], v[24:25]
	v_mov_b32_dpp v53, v43 row_ror:15 row_mask:0xf bank_mask:0xf
	v_mul_f32_e32 v50, 0xbfb8aa3b, v24
	v_mul_f32_e32 v51, 0xbfb8aa3b, v25
	v_exp_f32_e32 v50, v50
	v_exp_f32_e32 v51, v51
	v_cndmask_b32_e64 v57, v98, v52, s[6:7]
	v_add_f32_e32 v50, 1.0, v50
	v_add_f32_e32 v51, 1.0, v51
	v_rcp_f32_e32 v50, v50
	v_rcp_f32_e32 v51, v51
	s_nop 0
	v_pk_mul_f32 v[24:25], v[24:25], v[50:51]
	s_nop 0
	v_pk_mul_f32 v[50:51], v[26:27], v[24:25]
	v_cvt_pk_bf16_f32 v25, v30, v31
	v_mov_b32_dpp v30, v44 row_ror:1 row_mask:0xf bank_mask:0xf
	v_cvt_pk_bf16_f32 v27, v50, v51
	v_mov_b32_dpp v50, v40 row_ror:15 row_mask:0xf bank_mask:0xf
	v_cvt_pk_bf16_f32 v24, v28, v29
	v_cvt_pk_bf16_f32 v26, v48, v49
	global_store_dwordx4 v[124:125], v[24:27], off offset:256
	v_lshlrev_b32_e32 v28, 16, v44
	v_and_b32_e32 v29, 0xffff0000, v44
	v_cndmask_b32_e64 v25, v30, v58, s[4:5]
	v_lshlrev_b32_e32 v24, 16, v25
	v_and_b32_e32 v25, 0xffff0000, v25
	v_cndmask_b32_e64 v27, v96, v50, s[6:7]
	v_pk_mul_f32 v[24:25], v[92:93], v[24:25]
	v_lshlrev_b32_e32 v26, 16, v27
	v_and_b32_e32 v27, 0xffff0000, v27
	v_pk_fma_f32 v[24:25], v[84:85], v[28:29], v[24:25]
	v_mov_b32_dpp v31, v45 row_ror:1 row_mask:0xf bank_mask:0xf
	v_pk_fma_f32 v[24:25], v[80:81], v[26:27], v[24:25]
	v_mov_b32_dpp v51, v41 row_ror:15 row_mask:0xf bank_mask:0xf
	v_pk_add_f32 v[24:25], v[88:89], v[24:25]
	v_lshlrev_b32_e32 v28, 16, v45
	v_mul_f32_e32 v26, 0xbfb8aa3b, v24
	v_mul_f32_e32 v27, 0xbfb8aa3b, v25
	v_exp_f32_e32 v26, v26
	v_exp_f32_e32 v27, v27
	v_cndmask_b32_e64 v54, v31, v59, s[4:5]
	v_cndmask_b32_e64 v55, v97, v51, s[6:7]
	v_add_f32_e32 v26, 1.0, v26
	v_add_f32_e32 v27, 1.0, v27
	v_rcp_f32_e32 v26, v26
	v_rcp_f32_e32 v27, v27
	v_and_b32_e32 v29, 0xffff0000, v45
	v_mov_b32_dpp v48, v46 row_ror:1 row_mask:0xf bank_mask:0xf
	v_mov_b32_dpp v49, v47 row_ror:1 row_mask:0xf bank_mask:0xf
	v_pk_mul_f32 v[24:25], v[24:25], v[26:27]
	v_lshlrev_b32_e32 v26, 16, v55
	v_pk_mul_f32 v[20:21], v[20:21], v[24:25]
	v_lshlrev_b32_e32 v24, 16, v54
	v_and_b32_e32 v25, 0xffff0000, v54
	v_pk_mul_f32 v[24:25], v[94:95], v[24:25]
	v_and_b32_e32 v27, 0xffff0000, v55
	v_pk_fma_f32 v[24:25], v[86:87], v[28:29], v[24:25]
	v_cndmask_b32_e64 v56, v48, v60, s[4:5]
	v_pk_fma_f32 v[24:25], v[82:83], v[26:27], v[24:25]
	v_lshlrev_b32_e32 v28, 16, v46
	v_pk_add_f32 v[24:25], v[90:91], v[24:25]
	v_and_b32_e32 v29, 0xffff0000, v46
	v_mul_f32_e32 v26, 0xbfb8aa3b, v24
	v_mul_f32_e32 v27, 0xbfb8aa3b, v25
	v_exp_f32_e32 v26, v26
	v_exp_f32_e32 v27, v27
	v_cndmask_b32_e64 v58, v49, v62, s[4:5]
	v_cndmask_b32_e64 v59, v99, v53, s[6:7]
	v_add_f32_e32 v26, 1.0, v26
	v_add_f32_e32 v27, 1.0, v27
	v_rcp_f32_e32 v26, v26
	v_rcp_f32_e32 v27, v27
	s_nop 0
	v_pk_mul_f32 v[24:25], v[24:25], v[26:27]
	s_nop 0
	v_pk_mul_f32 v[22:23], v[22:23], v[24:25]
	v_lshlrev_b32_e32 v24, 16, v56
	v_and_b32_e32 v25, 0xffff0000, v56
	v_pk_mul_f32 v[24:25], v[76:77], v[24:25]
	v_lshlrev_b32_e32 v26, 16, v57
	v_and_b32_e32 v27, 0xffff0000, v57
	v_pk_fma_f32 v[24:25], v[68:69], v[28:29], v[24:25]
	v_lshlrev_b32_e32 v28, 16, v47
	v_pk_fma_f32 v[24:25], v[64:65], v[26:27], v[24:25]
	v_and_b32_e32 v29, 0xffff0000, v47
	v_pk_add_f32 v[24:25], v[72:73], v[24:25]
	s_nop 0
	v_mul_f32_e32 v26, 0xbfb8aa3b, v24
	v_mul_f32_e32 v27, 0xbfb8aa3b, v25
	v_exp_f32_e32 v26, v26
	v_exp_f32_e32 v27, v27
	v_add_f32_e32 v26, 1.0, v26
	v_add_f32_e32 v27, 1.0, v27
	v_rcp_f32_e32 v26, v26
	v_rcp_f32_e32 v27, v27
	s_nop 0
	v_pk_mul_f32 v[24:25], v[24:25], v[26:27]
	s_nop 0
	v_pk_mul_f32 v[24:25], v[16:17], v[24:25]
	v_lshlrev_b32_e32 v16, 16, v58
	v_and_b32_e32 v17, 0xffff0000, v58
	v_pk_mul_f32 v[16:17], v[78:79], v[16:17]
	v_lshlrev_b32_e32 v26, 16, v59
	v_and_b32_e32 v27, 0xffff0000, v59
	v_pk_fma_f32 v[16:17], v[70:71], v[28:29], v[16:17]
	v_mov_b32_dpp v28, v34 row_ror:15 row_mask:0xf bank_mask:0xf
	v_pk_fma_f32 v[16:17], v[66:67], v[26:27], v[16:17]
	v_mov_b32_dpp v29, v35 row_ror:15 row_mask:0xf bank_mask:0xf
	v_pk_add_f32 v[16:17], v[74:75], v[16:17]
	v_cndmask_b32_e64 v45, v52, v28, s[6:7]
	v_mul_f32_e32 v26, 0xbfb8aa3b, v16
	v_mul_f32_e32 v27, 0xbfb8aa3b, v17
	v_exp_f32_e32 v26, v26
	v_exp_f32_e32 v27, v27
	v_cndmask_b32_e64 v47, v53, v29, s[6:7]
	v_add_f32_e32 v26, 1.0, v26
	v_add_f32_e32 v27, 1.0, v27
	v_rcp_f32_e32 v26, v26
	v_rcp_f32_e32 v27, v27
	s_nop 0
	v_pk_mul_f32 v[16:17], v[16:17], v[26:27]
	s_nop 0
	v_pk_mul_f32 v[26:27], v[18:19], v[16:17]
	v_cvt_pk_bf16_f32 v17, v22, v23
	v_mov_b32_dpp v22, v40 row_ror:1 row_mask:0xf bank_mask:0xf
	v_cvt_pk_bf16_f32 v19, v26, v27
	v_mov_b32_dpp v26, v32 row_ror:15 row_mask:0xf bank_mask:0xf
	v_cvt_pk_bf16_f32 v16, v20, v21
	v_cvt_pk_bf16_f32 v18, v24, v25
	global_store_dwordx4 v[126:127], v[16:19], off offset:256
	v_lshlrev_b32_e32 v20, 16, v40
	v_and_b32_e32 v21, 0xffff0000, v40
	v_cndmask_b32_e64 v17, v22, v30, s[4:5]
	v_lshlrev_b32_e32 v16, 16, v17
	v_and_b32_e32 v17, 0xffff0000, v17
	v_cndmask_b32_e64 v19, v50, v26, s[6:7]
	v_pk_mul_f32 v[16:17], v[92:93], v[16:17]
	v_lshlrev_b32_e32 v18, 16, v19
	v_and_b32_e32 v19, 0xffff0000, v19
	v_pk_fma_f32 v[16:17], v[84:85], v[20:21], v[16:17]
	v_mov_b32_dpp v23, v41 row_ror:1 row_mask:0xf bank_mask:0xf
	v_pk_fma_f32 v[16:17], v[80:81], v[18:19], v[16:17]
	v_mov_b32_dpp v27, v33 row_ror:15 row_mask:0xf bank_mask:0xf
	v_pk_add_f32 v[16:17], v[88:89], v[16:17]
	v_lshlrev_b32_e32 v20, 16, v41
	v_mul_f32_e32 v18, 0xbfb8aa3b, v16
	v_mul_f32_e32 v19, 0xbfb8aa3b, v17
	v_exp_f32_e32 v18, v18
	v_exp_f32_e32 v19, v19
	v_cndmask_b32_e64 v30, v23, v31, s[4:5]
	v_cndmask_b32_e64 v31, v51, v27, s[6:7]
	v_add_f32_e32 v18, 1.0, v18
	v_add_f32_e32 v19, 1.0, v19
	v_rcp_f32_e32 v18, v18
	v_rcp_f32_e32 v19, v19
	v_and_b32_e32 v21, 0xffff0000, v41
	v_mov_b32_dpp v24, v42 row_ror:1 row_mask:0xf bank_mask:0xf
	v_mov_b32_dpp v25, v43 row_ror:1 row_mask:0xf bank_mask:0xf
	v_pk_mul_f32 v[16:17], v[16:17], v[18:19]
	v_lshlrev_b32_e32 v18, 16, v31
	v_pk_mul_f32 v[12:13], v[12:13], v[16:17]
	v_lshlrev_b32_e32 v16, 16, v30
	v_and_b32_e32 v17, 0xffff0000, v30
	v_pk_mul_f32 v[16:17], v[94:95], v[16:17]
	v_and_b32_e32 v19, 0xffff0000, v31
	v_pk_fma_f32 v[16:17], v[86:87], v[20:21], v[16:17]
	v_cndmask_b32_e64 v44, v24, v48, s[4:5]
	v_pk_fma_f32 v[16:17], v[82:83], v[18:19], v[16:17]
	v_lshlrev_b32_e32 v20, 16, v42
	v_pk_add_f32 v[16:17], v[90:91], v[16:17]
	v_and_b32_e32 v21, 0xffff0000, v42
	v_mul_f32_e32 v18, 0xbfb8aa3b, v16
	v_mul_f32_e32 v19, 0xbfb8aa3b, v17
	v_exp_f32_e32 v18, v18
	v_exp_f32_e32 v19, v19
	v_cndmask_b32_e64 v46, v25, v49, s[4:5]
	v_add_f32_e32 v18, 1.0, v18
	v_add_f32_e32 v19, 1.0, v19
	v_rcp_f32_e32 v18, v18
	v_rcp_f32_e32 v19, v19
	s_nop 0
	v_pk_mul_f32 v[16:17], v[16:17], v[18:19]
	s_nop 0
	v_pk_mul_f32 v[14:15], v[14:15], v[16:17]
	v_lshlrev_b32_e32 v16, 16, v44
	v_and_b32_e32 v17, 0xffff0000, v44
	v_pk_mul_f32 v[16:17], v[76:77], v[16:17]
	v_lshlrev_b32_e32 v18, 16, v45
	v_and_b32_e32 v19, 0xffff0000, v45
	v_pk_fma_f32 v[16:17], v[68:69], v[20:21], v[16:17]
	v_lshlrev_b32_e32 v20, 16, v43
	v_pk_fma_f32 v[16:17], v[64:65], v[18:19], v[16:17]
	v_and_b32_e32 v21, 0xffff0000, v43
	v_pk_add_f32 v[16:17], v[72:73], v[16:17]
	s_nop 0
	v_mul_f32_e32 v18, 0xbfb8aa3b, v16
	v_mul_f32_e32 v19, 0xbfb8aa3b, v17
	v_exp_f32_e32 v18, v18
	v_exp_f32_e32 v19, v19
	v_add_f32_e32 v18, 1.0, v18
	v_add_f32_e32 v19, 1.0, v19
	v_rcp_f32_e32 v18, v18
	v_rcp_f32_e32 v19, v19
	s_nop 0
	v_pk_mul_f32 v[16:17], v[16:17], v[18:19]
	s_nop 0
	v_pk_mul_f32 v[16:17], v[8:9], v[16:17]
	v_lshlrev_b32_e32 v8, 16, v46
	v_and_b32_e32 v9, 0xffff0000, v46
	v_pk_mul_f32 v[8:9], v[78:79], v[8:9]
	v_lshlrev_b32_e32 v18, 16, v47
	v_and_b32_e32 v19, 0xffff0000, v47
	v_pk_fma_f32 v[8:9], v[70:71], v[20:21], v[8:9]
	s_nop 0
	v_pk_fma_f32 v[8:9], v[66:67], v[18:19], v[8:9]
	s_nop 0
	v_pk_add_f32 v[8:9], v[74:75], v[8:9]
	s_nop 0
	v_mul_f32_e32 v18, 0xbfb8aa3b, v8
	v_mul_f32_e32 v19, 0xbfb8aa3b, v9
	v_exp_f32_e32 v18, v18
	v_exp_f32_e32 v19, v19
	v_add_f32_e32 v18, 1.0, v18
	v_add_f32_e32 v19, 1.0, v19
	v_rcp_f32_e32 v18, v18
	v_rcp_f32_e32 v19, v19
	s_nop 0
	v_pk_mul_f32 v[8:9], v[8:9], v[18:19]
	s_nop 0
	v_pk_mul_f32 v[18:19], v[10:11], v[8:9]
	v_cvt_pk_bf16_f32 v8, v12, v13
	v_cvt_pk_bf16_f32 v9, v14, v15
	v_cvt_pk_bf16_f32 v10, v16, v17
	v_cvt_pk_bf16_f32 v11, v18, v19
	global_store_dwordx4 v[132:133], v[8:11], off offset:256
	ds_bpermute_b32 v8, v193, v32
	ds_bpermute_b32 v9, v193, v33
	v_mov_b32_dpp v10, v34 row_ror:1 row_mask:0xf bank_mask:0xf
	v_mov_b32_dpp v11, v35 row_ror:1 row_mask:0xf bank_mask:0xf
	s_waitcnt vmcnt(3)
	v_cndmask_b32_e64 v12, v39, 0, vcc
	s_waitcnt lgkmcnt(0)
	v_cndmask_b32_e64 v16, v8, v22, s[4:5]
	v_cndmask_b32_e64 v13, v38, 0, vcc
	v_cndmask_b32_e64 v15, v36, 0, vcc
	v_cndmask_b32_e64 v17, v9, v23, s[4:5]
	v_lshlrev_b32_e32 v8, 16, v16
	v_and_b32_e32 v9, 0xffff0000, v16
	v_cndmask_b32_e64 v15, v26, v15, s[6:7]
	v_cndmask_b32_e64 v19, v28, v13, s[6:7]
	v_cndmask_b32_e64 v21, v29, v12, s[6:7]
	v_pk_mul_f32 v[8:9], v[92:93], v[8:9]
	v_lshlrev_b32_e32 v12, 16, v32
	v_and_b32_e32 v13, 0xffff0000, v32
	v_cndmask_b32_e64 v18, v10, v24, s[4:5]
	v_cndmask_b32_e64 v20, v11, v25, s[4:5]
	v_lshlrev_b32_e32 v10, 16, v15
	v_and_b32_e32 v11, 0xffff0000, v15
	v_pk_fma_f32 v[8:9], v[84:85], v[12:13], v[8:9]
	v_cndmask_b32_e64 v14, v37, 0, vcc
	v_pk_fma_f32 v[8:9], v[80:81], v[10:11], v[8:9]
	v_cndmask_b32_e64 v14, v27, v14, s[6:7]
	v_pk_add_f32 v[8:9], v[88:89], v[8:9]
	v_lshlrev_b32_e32 v12, 16, v33
	v_mul_f32_e32 v10, 0xbfb8aa3b, v8
	v_mul_f32_e32 v11, 0xbfb8aa3b, v9
	v_exp_f32_e32 v10, v10
	v_exp_f32_e32 v11, v11
	v_and_b32_e32 v13, 0xffff0000, v33
	s_andn2_b64 vcc, exec, s[68:69]
	v_add_f32_e32 v10, 1.0, v10
	v_add_f32_e32 v11, 1.0, v11
	v_rcp_f32_e32 v10, v10
	v_rcp_f32_e32 v11, v11
	s_nop 0
	v_pk_mul_f32 v[8:9], v[8:9], v[10:11]
	s_nop 0
	v_pk_mul_f32 v[4:5], v[4:5], v[8:9]
	v_lshlrev_b32_e32 v8, 16, v17
	v_and_b32_e32 v9, 0xffff0000, v17
	v_pk_mul_f32 v[8:9], v[94:95], v[8:9]
	v_lshlrev_b32_e32 v10, 16, v14
	v_and_b32_e32 v11, 0xffff0000, v14
	v_pk_fma_f32 v[8:9], v[86:87], v[12:13], v[8:9]
	v_lshlrev_b32_e32 v12, 16, v34
	v_pk_fma_f32 v[8:9], v[82:83], v[10:11], v[8:9]
	v_and_b32_e32 v13, 0xffff0000, v34
	v_pk_add_f32 v[8:9], v[90:91], v[8:9]
	s_nop 0
	v_mul_f32_e32 v10, 0xbfb8aa3b, v8
	v_mul_f32_e32 v11, 0xbfb8aa3b, v9
	v_exp_f32_e32 v10, v10
	v_exp_f32_e32 v11, v11
	v_add_f32_e32 v10, 1.0, v10
	v_add_f32_e32 v11, 1.0, v11
	v_rcp_f32_e32 v10, v10
	v_rcp_f32_e32 v11, v11
	s_nop 0
	v_pk_mul_f32 v[8:9], v[8:9], v[10:11]
	s_nop 0
	v_pk_mul_f32 v[6:7], v[6:7], v[8:9]
	v_lshlrev_b32_e32 v8, 16, v18
	v_and_b32_e32 v9, 0xffff0000, v18
	v_pk_mul_f32 v[8:9], v[76:77], v[8:9]
	v_lshlrev_b32_e32 v10, 16, v19
	v_and_b32_e32 v11, 0xffff0000, v19
	v_pk_fma_f32 v[8:9], v[68:69], v[12:13], v[8:9]
	v_lshlrev_b32_e32 v12, 16, v35
	v_pk_fma_f32 v[8:9], v[64:65], v[10:11], v[8:9]
	v_and_b32_e32 v13, 0xffff0000, v35
	v_pk_add_f32 v[8:9], v[72:73], v[8:9]
	s_nop 0
	v_mul_f32_e32 v10, 0xbfb8aa3b, v8
	v_mul_f32_e32 v11, 0xbfb8aa3b, v9
	v_exp_f32_e32 v10, v10
	v_exp_f32_e32 v11, v11
	v_add_f32_e32 v10, 1.0, v10
	v_add_f32_e32 v11, 1.0, v11
	v_rcp_f32_e32 v10, v10
	v_rcp_f32_e32 v11, v11
	s_nop 0
	v_pk_mul_f32 v[8:9], v[8:9], v[10:11]
	s_nop 0
	v_pk_mul_f32 v[8:9], v[0:1], v[8:9]
	v_lshlrev_b32_e32 v0, 16, v20
	v_and_b32_e32 v1, 0xffff0000, v20
	v_pk_mul_f32 v[0:1], v[78:79], v[0:1]
	v_lshlrev_b32_e32 v10, 16, v21
	v_and_b32_e32 v11, 0xffff0000, v21
	v_pk_fma_f32 v[0:1], v[70:71], v[12:13], v[0:1]
	s_nop 0
	v_pk_fma_f32 v[0:1], v[66:67], v[10:11], v[0:1]
	s_nop 0
	v_pk_add_f32 v[0:1], v[74:75], v[0:1]
	s_nop 0
	v_mul_f32_e32 v10, 0xbfb8aa3b, v0
	v_mul_f32_e32 v11, 0xbfb8aa3b, v1
	v_exp_f32_e32 v10, v10
	v_exp_f32_e32 v11, v11
	v_add_f32_e32 v10, 1.0, v10
	v_add_f32_e32 v11, 1.0, v11
	v_rcp_f32_e32 v10, v10
	v_rcp_f32_e32 v11, v11
	s_nop 0
	v_pk_mul_f32 v[0:1], v[0:1], v[10:11]
	s_nop 0
	v_pk_mul_f32 v[10:11], v[2:3], v[0:1]
	v_cvt_pk_bf16_f32 v0, v4, v5
	v_cvt_pk_bf16_f32 v1, v6, v7
	v_cvt_pk_bf16_f32 v2, v8, v9
	v_cvt_pk_bf16_f32 v3, v10, v11
	global_store_dwordx4 v[112:113], v[0:3], off offset:256
	s_cbranch_vccnz .LBB0_1053
	s_andn2_b64 vcc, exec, s[36:37]
	s_cbranch_vccnz .LBB0_1052
	s_barrier
	s_branch .LBB0_1052

.LBB0_1154:
	s_lshl_b32 s6, s20, 1
	s_or_b32 s13, s6, 1
	s_mul_i32 s7, s13, 0x3000
	s_mul_hi_u32 s6, s13, 0x3000
	s_add_u32 s7, s18, s7
	s_addc_u32 s6, s19, s6
	s_add_u32 s42, s7, 0x20000
	s_addc_u32 s43, s6, 0
	s_lshl_b32 s72, s20, 11
	s_lshl_b64 s[6:7], s[72:73], 2
	s_waitcnt lgkmcnt(0)
	s_add_u32 s36, s4, s6
	s_addc_u32 s37, s5, s7
	s_add_u32 s14, s18, 0x40000
	s_mul_i32 s4, s20, 0xc000
	s_addc_u32 s15, s19, 0
	s_add_i32 s6, s4, 0xc000
	s_and_b64 s[4:5], exec, s[8:9]
	s_cselect_b32 s72, 0, s6
	s_lshl_b64 s[4:5], s[72:73], 2
	s_add_u32 s6, s14, s4
	s_addc_u32 s7, s15, s5
	s_mul_hi_u32 s4, s13, 0x18000
	s_mul_i32 s13, s13, 0x18000
	s_add_u32 s40, s14, s13
	s_addc_u32 s41, s15, s4
	s_add_u32 s46, s18, 0x100000
	s_addc_u32 s47, s19, 0
	s_add_u32 s48, s18, 0x10200
	s_addc_u32 s49, s19, 0
	s_and_b32 s8, s3, 3
	s_lshl_b32 s3, s12, 6
	s_lshl_b32 s9, s12, 13
	s_lshl_b32 s13, s8, 12
	s_add_u32 s18, s18, 0x8800000
	s_addc_u32 s19, s19, 0
	s_add_i32 m0, s28, 0x18000
	v_lshl_add_u64 v[6:7], v[6:7], 0, s[74:75]
	s_waitcnt vmcnt(2)
	s_barrier
	global_load_lds_dwordx4 v[6:7], off
	v_lshl_add_u64 v[4:5], v[4:5], 0, s[74:75]
	s_add_i32 m0, s28, 0x1a000
	s_add_i32 s44, s28, 0x8000
	s_add_i32 s45, s28, 0xa000
	global_load_lds_dwordx4 v[4:5], off
	v_lshl_add_u64 v[0:1], v[0:1], 0, s[74:75]
	s_mov_b32 m0, s44
	s_add_u32 s4, s30, 0x160080
	global_load_lds_dwordx4 v[0:1], off
	v_lshl_add_u64 v[0:1], v[2:3], 0, s[74:75]
	s_mov_b32 m0, s45
	s_addc_u32 s5, s31, 0
	global_load_lds_dwordx4 v[0:1], off
	s_add_i32 m0, s28, 0x1c000
	v_lshl_add_u64 v[0:1], s[4:5], 0, v[176:177]
	global_load_lds_dwordx4 v[0:1], off
	v_lshl_add_u64 v[0:1], s[4:5], 0, v[182:183]
	s_add_i32 m0, s28, 0x1e000
	v_lshlrev_b32_e32 v5, 2, v15
	global_load_lds_dwordx4 v[0:1], off
	v_and_b32_e32 v0, 15, v15
	v_bfe_u32 v1, v15, 4, 2
	v_or_b32_e32 v184, s3, v0
	v_lshlrev_b32_e32 v2, 4, v1
	v_lshlrev_b32_e32 v3, 2, v184
	s_cmpk_lt_u32 s2, 0x100
	v_lshl_or_b32 v2, v0, 6, v2
	v_and_b32_e32 v4, 32, v3
	v_and_b32_e32 v5, 32, v5
	s_cselect_b64 s[52:53], -1, 0
	s_add_i32 s2, s3, 0x80
	v_bitop3_b32 v4, v2, s9, v4 bitop3:0xde
	v_bitop3_b32 v204, v2, s13, v5 bitop3:0xde
	v_lshlrev_b32_e32 v2, 4, v0
	v_ashrrev_i32_e32 v185, 31, v184
	v_or_b32_e32 v0, s2, v0
	s_ashr_i32 s2, s3, 31
	v_lshl_add_u64 v[186:187], v[184:185], 2, s[6:7]
	v_mov_b32_e32 v185, s2
	v_lshl_add_u64 v[188:189], v[184:185], 2, s[6:7]
	s_mov_b64 s[2:3], 0xc0
	v_lshl_add_u64 v[194:195], v[188:189], 0, s[2:3]
	s_lshl_b32 s2, s8, 2
	s_lshl_b32 s9, s12, 10
	s_add_i32 s2, s2, 0
	s_add_i32 s2, s2, s9
	s_add_i32 s6, s2, 0x20c00
	v_readlane_b32 s2, v254, 57
	s_movk_i32 s7, 0x1600
	v_lshlrev_b32_e32 v6, 3, v1
	v_cmp_eq_u32_e64 s[4:5], 0, v1
	v_lshl_add_u32 v209, v0, 2, s2
	v_lshrrev_b32_e32 v1, 1, v8
	v_mul_lo_u32 v0, v9, s7
	v_add_u32_e32 v185, s2, v3
	v_mad_u64_u32 v[0:1], s[2:3], v1, s97, v[0:1]
	v_or_b32_e32 v0, v0, v10
	v_lshl_or_b32 v205, s8, 5, v6
	v_add_lshl_u32 v0, v0, v11, 1
	v_mov_b32_e32 v1, v177
	s_mov_b64 s[8:9], 0x160080
	v_lshl_add_u64 v[196:197], v[0:1], 0, s[8:9]
	v_lshrrev_b32_e32 v1, 1, v12
	v_mul_lo_u32 v0, v13, s7
	v_mad_u64_u32 v[0:1], s[2:3], v1, s97, v[0:1]
	s_waitcnt vmcnt(6)
	s_cmp_eq_u64 s[16:17], 0
	v_or_b32_e32 v0, v0, v14
	s_cselect_b64 s[54:55], -1, 0
	s_cmp_lg_u64 s[16:17], 0
	v_add_lshl_u32 v0, v0, v16, 1
	v_mov_b32_e32 v1, v177
	s_mov_b32 s58, 0
	v_lshl_add_u64 v[190:191], v[188:189], 0, 64
	v_lshl_add_u64 v[192:193], v[188:189], 0, s[74:75]
	s_cselect_b64 s[56:57], -1, 0
	v_add_u32_e32 v206, 64, v185
	v_add_u32_e32 v207, 0x80, v185
	v_add_u32_e32 v208, 0xc0, v185
	v_add_u32_e32 v220, 64, v209
	v_add_u32_e32 v221, 0x80, v209
	v_add_u32_e32 v222, 0xc0, v209
	v_lshl_add_u64 v[198:199], v[0:1], 0, s[8:9]
	v_add_u32_e32 v223, 0, v4
	v_add_u32_e32 v224, s6, v2
	s_mov_b32 s60, s94
	s_mov_b32 s62, s90
	s_mov_b64 s[68:69], s[0:1]
	s_barrier
	s_branch .LBB0_1157
	s_nop 0
	s_nop 0
	s_nop 0
	s_nop 0
	s_nop 0
.LBB0_1155:
	s_mov_b64 s[0:1], 0
